# adds: barrier-adjacent setprio/wait cleanup in all GEMM loops, P0 rms gain loads hoisted + cache_k 2 rows per iteration, attention QK K-fragment reads issued before S init with counted LDS waits
# speedup vs baseline: 1.0159x; 1.0058x over previous
.LBB0_45:
	s_cmpk_gt_i32 s8, 0x47ff
	v_mov_b32_e32 v67, 0
	s_cbranch_scc1 .LBB0_50
	v_mbcnt_lo_u32_b32 v1, -1, 0
	v_mbcnt_hi_u32_b32 v2, -1, v1
	v_and_b32_e32 v1, 64, v2
	v_add_u32_e32 v3, 64, v1
	v_xor_b32_e32 v1, 1, v2
	v_cmp_lt_i32_e32 vcc, v1, v3
	v_xor_b32_e32 v4, 2, v2
	v_lshlrev_b32_e32 v66, 3, v196
	v_cndmask_b32_e32 v1, v2, v1, vcc
	v_cmp_lt_i32_e32 vcc, v4, v3
	v_lshl_add_u64 v[68:69], s[86:87], 0, v[66:67]
	v_lshlrev_b32_e32 v66, 4, v196
	v_cndmask_b32_e32 v4, v2, v4, vcc
	v_lshlrev_b32_e32 v96, 2, v4
	v_xor_b32_e32 v4, 4, v2
	v_cmp_lt_i32_e32 vcc, v4, v3
	v_lshl_add_u64 v[70:71], s[64:65], 0, v[66:67]
	s_mov_b64 s[0:1], 0x1000
	v_cndmask_b32_e32 v4, v2, v4, vcc
	v_lshl_add_u64 v[72:73], v[70:71], 0, s[0:1]
	s_mov_b64 s[0:1], 0x1400
	v_lshlrev_b32_e32 v97, 2, v4
	v_xor_b32_e32 v4, 8, v2
	v_lshl_add_u64 v[74:75], v[70:71], 0, s[0:1]
	s_mov_b64 s[0:1], 0x1800
	v_cmp_lt_i32_e32 vcc, v4, v3
	v_lshl_add_u64 v[76:77], v[70:71], 0, s[0:1]
	s_mov_b64 s[0:1], 0x1c00
	v_cndmask_b32_e32 v4, v2, v4, vcc
	v_lshl_add_u64 v[78:79], v[70:71], 0, s[0:1]
	s_mov_b64 s[0:1], 0x2000
	v_lshlrev_b32_e32 v98, 2, v4
	v_xor_b32_e32 v4, 16, v2
	v_lshl_add_u64 v[80:81], v[70:71], 0, s[0:1]
	s_mov_b64 s[0:1], 0x2400
	v_cmp_lt_i32_e32 vcc, v4, v3
	v_lshl_add_u64 v[82:83], v[70:71], 0, s[0:1]
	s_mov_b64 s[0:1], 0x2800
	v_cndmask_b32_e32 v4, v2, v4, vcc
	v_lshl_add_u64 v[84:85], v[70:71], 0, s[0:1]
	s_mov_b64 s[0:1], 0x2c00
	v_lshlrev_b32_e32 v99, 2, v4
	v_xor_b32_e32 v4, 32, v2
	v_lshl_add_u64 v[86:87], v[70:71], 0, s[0:1]
	s_mov_b64 s[0:1], 0x3000
	v_cmp_lt_i32_e32 vcc, v4, v3
	v_lshl_add_u64 v[88:89], v[70:71], 0, s[0:1]
	s_mov_b64 s[0:1], 0x3400
	v_cndmask_b32_e32 v2, v2, v4, vcc
	v_lshl_add_u64 v[90:91], v[70:71], 0, s[0:1]
	s_mov_b64 s[0:1], 0x3800
	s_ashr_i32 s9, s8, 31
	v_lshlrev_b32_e32 v100, 2, v2
	v_lshl_add_u64 v[92:93], v[70:71], 0, s[0:1]
	v_mov_b32_e32 v2, 0x3c00
	s_ashr_i32 s11, s10, 31
	s_lshl_b64 s[0:1], s[8:9], 14
	v_lshl_or_b32 v2, v0, 4, v2
	v_mov_b32_e32 v3, v67
	s_add_u32 s12, s52, s0
	s_mov_b32 s5, 0
	v_lshlrev_b32_e32 v1, 2, v1
	v_lshl_add_u64 v[94:95], s[64:65], 0, v[2:3]
	s_addc_u32 s13, s53, s1
	s_lshl_b64 s[14:15], s[10:11], 14
	s_movk_i32 s20, 0x1000
	s_movk_i32 s21, 0x2000
	s_movk_i32 s28, 0x3000
	v_mov_b32_e32 v101, 0x358637bd
	s_mov_b32 s29, 0xf800000
	v_mov_b32_e32 v102, 0x260
	s_mov_b64 s[16:17], s[8:9]
	global_load_dwordx4 v[122:125], v[70:71], off
	global_load_dwordx4 v[126:129], v[70:71], off offset:1024
	global_load_dwordx4 v[130:133], v[70:71], off offset:2048
	global_load_dwordx4 v[134:137], v[70:71], off offset:3072
	global_load_dwordx4 v[138:141], v[72:73], off
	global_load_dwordx4 v[142:145], v[74:75], off
	global_load_dwordx4 v[146:149], v[76:77], off
	global_load_dwordx4 v[150:153], v[78:79], off
	global_load_dwordx4 v[154:157], v[80:81], off
	global_load_dwordx4 v[158:161], v[82:83], off
	global_load_dwordx4 v[162:165], v[84:85], off
	global_load_dwordx4 v[166:169], v[86:87], off
	global_load_dwordx4 v[170:173], v[88:89], off
	global_load_dwordx4 v[174:177], v[90:91], off
	global_load_dwordx4 v[178:181], v[92:93], off
	global_load_dwordx4 v[182:185], v[94:95], off
	s_waitcnt vmcnt(0)
	s_branch .LBB0_48
.LBB0_47:
	v_lshl_add_u64 v[2:3], s[0:1], 0, v[66:67]
	v_add_co_u32_e32 v4, vcc, s21, v2
	global_load_dwordx4 v[58:61], v66, s[0:1]
	global_load_dwordx4 v[46:49], v66, s[0:1] offset:1024
	global_load_dwordx4 v[38:41], v66, s[0:1] offset:2048
	global_load_dwordx4 v[26:29], v66, s[0:1] offset:3072
	v_addc_co_u32_e32 v5, vcc, 0, v3, vcc
	global_load_dwordx4 v[18:21], v[4:5], off offset:-4096
	v_add_co_u32_e32 v6, vcc, s20, v2
	s_waitcnt vmcnt(4)
	v_mul_f32_e32 v103, v59, v59
	v_addc_co_u32_e32 v7, vcc, 0, v3, vcc
	global_load_dwordx4 v[14:17], v[6:7], off offset:1024
	global_load_dwordx4 v[10:13], v[6:7], off offset:2048
	s_nop 0
	global_load_dwordx4 v[6:9], v[6:7], off offset:3072
	s_nop 0
	global_load_dwordx4 v[62:65], v[4:5], off
	global_load_dwordx4 v[54:57], v[4:5], off offset:1024
	global_load_dwordx4 v[50:53], v[4:5], off offset:2048
	global_load_dwordx4 v[42:45], v[4:5], off offset:3072
	v_add_co_u32_e32 v22, vcc, s28, v2
	v_mul_f32_e32 v104, v61, v61
	s_nop 0
	v_addc_co_u32_e32 v23, vcc, 0, v3, vcc
	global_load_dwordx4 v[30:33], v[22:23], off
	global_load_dwordx4 v[34:37], v[22:23], off offset:1024
	global_load_dwordx4 v[2:5], v[22:23], off offset:3072
	s_nop 0
	global_load_dwordx4 v[22:25], v[22:23], off offset:2048
	s_waitcnt vmcnt(14)
	v_mul_f32_e32 v105, v47, v47
	v_mul_f32_e32 v106, v49, v49
	s_waitcnt vmcnt(13)
	v_mul_f32_e32 v107, v39, v39
	v_mul_f32_e32 v108, v41, v41
	v_fmac_f32_e32 v103, v58, v58
	v_fmac_f32_e32 v104, v60, v60
	v_fmac_f32_e32 v105, v46, v46
	v_fmac_f32_e32 v106, v48, v48
	s_waitcnt vmcnt(12)
	v_mul_f32_e32 v109, v27, v27
	v_mul_f32_e32 v110, v29, v29
	v_fmac_f32_e32 v107, v38, v38
	v_fmac_f32_e32 v108, v40, v40
	v_add_f32_e32 v103, v103, v104
	v_add_f32_e32 v104, v105, v106
	v_fmac_f32_e32 v109, v26, v26
	v_fmac_f32_e32 v110, v28, v28
	v_add_f32_e32 v105, v107, v108
	s_waitcnt vmcnt(11)
	v_mul_f32_e32 v107, v19, v19
	v_mul_f32_e32 v108, v21, v21
	v_add_f32_e32 v103, v103, v104
	v_add_f32_e32 v106, v109, v110
	v_fmac_f32_e32 v107, v18, v18
	v_fmac_f32_e32 v108, v20, v20
	v_add_f32_e32 v103, v103, v105
	v_add_f32_e32 v104, v107, v108
	v_add_f32_e32 v103, v103, v106
	v_add_f32_e32 v103, v103, v104
	s_waitcnt vmcnt(10)
	v_mul_f32_e32 v109, v15, v15
	v_mul_f32_e32 v110, v17, v17
	s_waitcnt vmcnt(9)
	v_mul_f32_e32 v111, v11, v11
	v_mul_f32_e32 v112, v13, v13
	v_fmac_f32_e32 v109, v14, v14
	v_fmac_f32_e32 v110, v16, v16
	s_waitcnt vmcnt(8)
	v_mul_f32_e32 v113, v7, v7
	v_mul_f32_e32 v114, v9, v9
	v_fmac_f32_e32 v111, v10, v10
	v_fmac_f32_e32 v112, v12, v12
	v_add_f32_e32 v105, v109, v110
	s_waitcnt vmcnt(7)
	v_mul_f32_e32 v115, v63, v63
	v_mul_f32_e32 v116, v65, v65
	v_fmac_f32_e32 v113, v6, v6
	v_fmac_f32_e32 v114, v8, v8
	v_add_f32_e32 v107, v111, v112
	v_add_f32_e32 v103, v103, v105
	s_waitcnt vmcnt(6)
	v_mul_f32_e32 v117, v55, v55
	v_mul_f32_e32 v118, v57, v57
	v_fmac_f32_e32 v115, v62, v62
	v_fmac_f32_e32 v116, v64, v64
	v_add_f32_e32 v108, v113, v114
	v_add_f32_e32 v103, v103, v107
	s_waitcnt vmcnt(5)
	v_mul_f32_e32 v119, v51, v51
	v_mul_f32_e32 v120, v53, v53
	v_fmac_f32_e32 v117, v54, v54
	v_fmac_f32_e32 v118, v56, v56
	v_add_f32_e32 v109, v115, v116
	v_add_f32_e32 v103, v103, v108
	v_fmac_f32_e32 v119, v50, v50
	v_fmac_f32_e32 v120, v52, v52
	v_add_f32_e32 v110, v117, v118
	v_add_f32_e32 v103, v103, v109
	s_waitcnt vmcnt(4)
	v_mul_f32_e32 v104, v43, v43
	v_mul_f32_e32 v105, v45, v45
	v_add_f32_e32 v111, v119, v120
	v_add_f32_e32 v103, v103, v110
	v_fmac_f32_e32 v104, v42, v42
	v_fmac_f32_e32 v105, v44, v44
	v_add_f32_e32 v103, v103, v111
	v_add_f32_e32 v104, v104, v105
	v_add_f32_e32 v103, v103, v104
	s_waitcnt vmcnt(3)
	v_mul_f32_e32 v104, v31, v31
	v_mul_f32_e32 v105, v33, v33
	v_fmac_f32_e32 v104, v30, v30
	v_fmac_f32_e32 v105, v32, v32
	v_add_f32_e32 v104, v104, v105
	v_add_f32_e32 v103, v103, v104
	s_waitcnt vmcnt(2)
	v_mul_f32_e32 v104, v35, v35
	v_mul_f32_e32 v105, v37, v37
	v_fmac_f32_e32 v104, v34, v34
	v_fmac_f32_e32 v105, v36, v36
	v_add_f32_e32 v104, v104, v105
	v_add_f32_e32 v103, v103, v104
	s_waitcnt vmcnt(0)
	v_mul_f32_e32 v104, v23, v23
	v_mul_f32_e32 v105, v25, v25
	v_fmac_f32_e32 v104, v22, v22
	v_fmac_f32_e32 v105, v24, v24
	v_add_f32_e32 v104, v104, v105
	v_add_f32_e32 v103, v103, v104
	v_mul_f32_e32 v108, v3, v3
	v_mul_f32_e32 v109, v5, v5
	v_fmac_f32_e32 v108, v2, v2
	v_fmac_f32_e32 v109, v4, v4
	v_add_f32_e32 v108, v108, v109
	v_add_f32_e32 v103, v103, v108
	ds_bpermute_b32 v108, v1, v103
	s_waitcnt lgkmcnt(0)
	v_add_f32_e32 v103, v103, v108
	ds_bpermute_b32 v108, v96, v103
	s_waitcnt lgkmcnt(0)
	v_add_f32_e32 v103, v103, v108
	ds_bpermute_b32 v108, v97, v103
	s_waitcnt lgkmcnt(0)
	v_add_f32_e32 v103, v103, v108
	ds_bpermute_b32 v108, v98, v103
	s_waitcnt lgkmcnt(0)
	v_add_f32_e32 v103, v103, v108
	ds_bpermute_b32 v108, v99, v103
	s_waitcnt lgkmcnt(0)
	v_add_f32_e32 v103, v103, v108
	ds_bpermute_b32 v108, v100, v103
	s_waitcnt lgkmcnt(0)
	v_add_f32_e32 v103, v103, v108
	v_fmamk_f32 v103, v103, 0x39800000, v101
	v_mul_f32_e32 v108, 0x4f800000, v103
	v_cmp_gt_f32_e32 vcc, s29, v103
	s_nop 1
	v_cndmask_b32_e32 v103, v103, v108, vcc
	v_sqrt_f32_e32 v108, v103
	s_nop 0
	v_add_u32_e32 v109, -1, v108
	v_fma_f32 v110, -v109, v108, v103
	v_cmp_ge_f32_e64 s[0:1], 0, v110
	v_add_u32_e32 v110, 1, v108
	s_nop 0
	v_cndmask_b32_e64 v109, v108, v109, s[0:1]
	v_fma_f32 v108, -v110, v108, v103
	v_cmp_lt_f32_e64 s[0:1], 0, v108
	s_nop 1
	v_cndmask_b32_e64 v108, v109, v110, s[0:1]
	v_mul_f32_e32 v109, 0x37800000, v108
	v_cndmask_b32_e32 v108, v108, v109, vcc
	v_cmp_class_f32_e32 vcc, v103, v102
	s_nop 1
	v_cndmask_b32_e32 v103, v108, v103, vcc
	v_div_scale_f32 v108, s[0:1], v103, v103, 1.0
	v_rcp_f32_e32 v109, v108
	s_lshl_b64 s[0:1], s[18:19], 13
	s_add_u32 s16, s16, s10
	s_addc_u32 s17, s17, s11
	v_fma_f32 v110, -v108, v109, 1.0
	v_fmac_f32_e32 v109, v110, v109
	v_div_scale_f32 v110, vcc, 1.0, v103, 1.0
	v_mul_f32_e32 v111, v110, v109
	v_fma_f32 v112, -v108, v111, v110
	v_fmac_f32_e32 v111, v112, v109
	v_fma_f32 v108, -v108, v111, v110
	v_div_fmas_f32 v108, v108, v109, v111
	v_div_fixup_f32 v103, v108, v103, 1.0
	v_mul_f32_e32 v58, v103, v58
	v_mul_f32_e32 v59, v103, v59
	v_mul_f32_e32 v60, v103, v60
	v_mul_f32_e32 v61, v103, v61
	v_mul_f32_e32 v58, v122, v58
	v_mul_f32_e32 v59, v123, v59
	v_lshl_add_u64 v[104:105], v[68:69], 0, s[0:1]
	v_mul_f32_e32 v60, v124, v60
	v_mul_f32_e32 v61, v125, v61
	v_cvt_pk_bf16_f32 v58, v58, v59
	v_cvt_pk_bf16_f32 v59, v60, v61
	global_store_dwordx2 v[104:105], v[58:59], off
	v_mul_f32_e32 v46, v103, v46
	v_mul_f32_e32 v47, v103, v47
	v_mul_f32_e32 v48, v103, v48
	v_mul_f32_e32 v49, v103, v49
	v_mul_f32_e32 v38, v103, v38
	v_mul_f32_e32 v39, v103, v39
	v_mul_f32_e32 v40, v103, v40
	v_mul_f32_e32 v41, v103, v41
	v_mul_f32_e32 v26, v103, v26
	v_mul_f32_e32 v27, v103, v27
	v_mul_f32_e32 v28, v103, v28
	v_mul_f32_e32 v29, v103, v29
	v_mul_f32_e32 v18, v103, v18
	v_mul_f32_e32 v19, v103, v19
	v_mul_f32_e32 v20, v103, v20
	v_mul_f32_e32 v21, v103, v21
	v_mul_f32_e32 v14, v103, v14
	v_mul_f32_e32 v15, v103, v15
	v_mul_f32_e32 v16, v103, v16
	v_mul_f32_e32 v17, v103, v17
	v_mul_f32_e32 v10, v103, v10
	v_mul_f32_e32 v11, v103, v11
	v_mul_f32_e32 v12, v103, v12
	v_mul_f32_e32 v13, v103, v13
	v_mul_f32_e32 v6, v103, v6
	v_mul_f32_e32 v7, v103, v7
	v_mul_f32_e32 v8, v103, v8
	v_mul_f32_e32 v9, v103, v9
	s_add_u32 s12, s12, s14
	s_addc_u32 s13, s13, s15
	v_mul_f32_e32 v2, v103, v2
	v_mul_f32_e32 v3, v103, v3
	v_mul_f32_e32 v4, v103, v4
	v_mul_f32_e32 v5, v103, v5
	s_cmpk_gt_i32 s16, 0x47ff
	v_mul_f32_e32 v46, v126, v46
	v_mul_f32_e32 v47, v127, v47
	v_mul_f32_e32 v48, v128, v48
	v_mul_f32_e32 v49, v129, v49
	v_cvt_pk_bf16_f32 v46, v46, v47
	v_cvt_pk_bf16_f32 v47, v48, v49
	global_store_dwordx2 v[104:105], v[46:47], off offset:512
	v_mul_f32_e32 v38, v130, v38
	v_mul_f32_e32 v39, v131, v39
	v_mul_f32_e32 v40, v132, v40
	v_mul_f32_e32 v41, v133, v41
	v_cvt_pk_bf16_f32 v38, v38, v39
	v_cvt_pk_bf16_f32 v39, v40, v41
	global_store_dwordx2 v[104:105], v[38:39], off offset:1024
	v_mul_f32_e32 v26, v134, v26
	v_mul_f32_e32 v27, v135, v27
	v_mul_f32_e32 v28, v136, v28
	v_mul_f32_e32 v29, v137, v29
	v_cvt_pk_bf16_f32 v26, v26, v27
	v_cvt_pk_bf16_f32 v27, v28, v29
	global_store_dwordx2 v[104:105], v[26:27], off offset:1536
	v_mul_f32_e32 v18, v138, v18
	v_mul_f32_e32 v19, v139, v19
	v_mul_f32_e32 v20, v140, v20
	v_mul_f32_e32 v21, v141, v21
	v_cvt_pk_bf16_f32 v18, v18, v19
	v_cvt_pk_bf16_f32 v19, v20, v21
	global_store_dwordx2 v[104:105], v[18:19], off offset:2048
	v_mul_f32_e32 v14, v142, v14
	v_mul_f32_e32 v15, v143, v15
	v_mul_f32_e32 v16, v144, v16
	v_mul_f32_e32 v17, v145, v17
	v_cvt_pk_bf16_f32 v14, v14, v15
	v_cvt_pk_bf16_f32 v15, v16, v17
	global_store_dwordx2 v[104:105], v[14:15], off offset:2560
	v_mul_f32_e32 v10, v146, v10
	v_mul_f32_e32 v11, v147, v11
	v_mul_f32_e32 v12, v148, v12
	v_mul_f32_e32 v13, v149, v13
	v_cvt_pk_bf16_f32 v10, v10, v11
	v_cvt_pk_bf16_f32 v11, v12, v13
	global_store_dwordx2 v[104:105], v[10:11], off offset:3072
	v_mul_f32_e32 v14, v103, v64
	v_mul_f32_e32 v15, v103, v65
	v_mul_f32_e32 v6, v150, v6
	v_mul_f32_e32 v7, v151, v7
	v_mul_f32_e32 v8, v152, v8
	v_mul_f32_e32 v9, v153, v9
	v_cvt_pk_bf16_f32 v6, v6, v7
	v_cvt_pk_bf16_f32 v7, v8, v9
	global_store_dwordx2 v[104:105], v[6:7], off offset:3584
	v_add_co_u32_e32 v10, vcc, s20, v104
	v_mul_f32_e32 v12, v103, v62
	v_mul_f32_e32 v13, v103, v63
	v_addc_co_u32_e32 v11, vcc, 0, v105, vcc
	v_mul_f32_e32 v6, v154, v12
	v_mul_f32_e32 v7, v155, v13
	v_mul_f32_e32 v8, v156, v14
	v_mul_f32_e32 v9, v157, v15
	v_cvt_pk_bf16_f32 v6, v6, v7
	v_cvt_pk_bf16_f32 v7, v8, v9
	global_store_dwordx2 v[10:11], v[6:7], off
	v_mul_f32_e32 v12, v103, v54
	v_mul_f32_e32 v13, v103, v55
	v_mul_f32_e32 v14, v103, v56
	v_mul_f32_e32 v15, v103, v57
	v_mul_f32_e32 v6, v158, v12
	v_mul_f32_e32 v7, v159, v13
	v_mul_f32_e32 v8, v160, v14
	v_mul_f32_e32 v9, v161, v15
	v_cvt_pk_bf16_f32 v6, v6, v7
	v_cvt_pk_bf16_f32 v7, v8, v9
	global_store_dwordx2 v[10:11], v[6:7], off offset:512
	v_mul_f32_e32 v12, v103, v50
	v_mul_f32_e32 v13, v103, v51
	v_mul_f32_e32 v14, v103, v52
	v_mul_f32_e32 v15, v103, v53
	v_mul_f32_e32 v6, v162, v12
	v_mul_f32_e32 v7, v163, v13
	v_mul_f32_e32 v8, v164, v14
	v_mul_f32_e32 v9, v165, v15
	v_cvt_pk_bf16_f32 v6, v6, v7
	v_cvt_pk_bf16_f32 v7, v8, v9
	global_store_dwordx2 v[10:11], v[6:7], off offset:1024
	v_mul_f32_e32 v12, v103, v42
	v_mul_f32_e32 v13, v103, v43
	v_mul_f32_e32 v14, v103, v44
	v_mul_f32_e32 v15, v103, v45
	v_mul_f32_e32 v6, v166, v12
	v_mul_f32_e32 v7, v167, v13
	v_mul_f32_e32 v8, v168, v14
	v_mul_f32_e32 v9, v169, v15
	v_cvt_pk_bf16_f32 v6, v6, v7
	v_cvt_pk_bf16_f32 v7, v8, v9
	global_store_dwordx2 v[10:11], v[6:7], off offset:1536
	v_mul_f32_e32 v12, v103, v30
	v_mul_f32_e32 v13, v103, v31
	v_mul_f32_e32 v14, v103, v32
	v_mul_f32_e32 v15, v103, v33
	v_mul_f32_e32 v6, v170, v12
	v_mul_f32_e32 v7, v171, v13
	v_mul_f32_e32 v8, v172, v14
	v_mul_f32_e32 v9, v173, v15
	v_cvt_pk_bf16_f32 v6, v6, v7
	v_cvt_pk_bf16_f32 v7, v8, v9
	global_store_dwordx2 v[10:11], v[6:7], off offset:2048
	v_mul_f32_e32 v12, v103, v34
	v_mul_f32_e32 v13, v103, v35
	v_mul_f32_e32 v14, v103, v36
	v_mul_f32_e32 v15, v103, v37
	v_mul_f32_e32 v6, v174, v12
	v_mul_f32_e32 v7, v175, v13
	v_mul_f32_e32 v8, v176, v14
	v_mul_f32_e32 v9, v177, v15
	v_cvt_pk_bf16_f32 v6, v6, v7
	v_cvt_pk_bf16_f32 v7, v8, v9
	global_store_dwordx2 v[10:11], v[6:7], off offset:2560
	v_mul_f32_e32 v12, v103, v22
	v_mul_f32_e32 v13, v103, v23
	v_mul_f32_e32 v14, v103, v24
	v_mul_f32_e32 v15, v103, v25
	v_mul_f32_e32 v6, v178, v12
	v_mul_f32_e32 v7, v179, v13
	v_mul_f32_e32 v8, v180, v14
	v_mul_f32_e32 v9, v181, v15
	v_cvt_pk_bf16_f32 v6, v6, v7
	v_cvt_pk_bf16_f32 v7, v8, v9
	global_store_dwordx2 v[10:11], v[6:7], off offset:3072
	v_mul_f32_e32 v2, v182, v2
	v_mul_f32_e32 v3, v183, v3
	v_mul_f32_e32 v4, v184, v4
	v_mul_f32_e32 v5, v185, v5
	v_cvt_pk_bf16_f32 v2, v2, v3
	v_cvt_pk_bf16_f32 v3, v4, v5
	global_store_dwordx2 v[10:11], v[2:3], off offset:3584
	s_cbranch_scc1 .LBB0_50

.LBB0_52:
	global_load_dwordx4 v[6:9], v[4:5], off offset:-2064
	global_load_dwordx4 v[10:13], v[4:5], off offset:-2048
	global_load_dwordx4 v[16:19], v[4:5], off offset:-16
	global_load_dwordx4 v[20:23], v[4:5], off
	v_lshl_add_u64 v[24:25], v[4:5], 0, s[0:1]
	s_ashr_i32 s5, s4, 11
	s_and_b32 s9, s4, 0x7ff
	s_mul_hi_i32 s11, s5, 0x840
	s_mulk_i32 s5, 0x840
	s_add_u32 s12, s5, s9
	s_addc_u32 s13, s11, 0
	s_lshl_b64 s[12:13], s[12:13], 11
	global_load_dwordx4 v[26:29], v[24:25], off offset:-2064
	global_load_dwordx4 v[30:33], v[24:25], off offset:-2048
	global_load_dwordx4 v[34:37], v[24:25], off offset:-16
	global_load_dwordx4 v[38:41], v[24:25], off
	v_lshl_add_u64 v[14:15], v[2:3], 0, s[12:13]
	s_add_i32 s4, s4, s10
	s_ashr_i32 s5, s4, 11
	s_and_b32 s9, s4, 0x7ff
	s_mul_hi_i32 s11, s5, 0x840
	s_mulk_i32 s5, 0x840
	s_add_u32 s12, s5, s9
	s_addc_u32 s13, s11, 0
	s_lshl_b64 s[12:13], s[12:13], 11
	v_lshl_add_u64 v[42:43], v[2:3], 0, s[12:13]
	v_lshl_add_u64 v[4:5], v[24:25], 0, s[0:1]
	s_add_i32 s4, s4, s10
	s_cmp_gt_i32 s4, 0xffff
	s_waitcnt vmcnt(7)
	v_cvt_pk_bf16_f32 v6, v6, v7
	v_cvt_pk_bf16_f32 v7, v8, v9
	s_waitcnt vmcnt(6)
	v_cvt_pk_bf16_f32 v8, v10, v11
	v_cvt_pk_bf16_f32 v9, v12, v13
	global_store_dwordx4 v[14:15], v[6:9], off
	s_waitcnt vmcnt(6)
	v_cvt_pk_bf16_f32 v16, v16, v17
	v_cvt_pk_bf16_f32 v17, v18, v19
	s_waitcnt vmcnt(5)
	v_cvt_pk_bf16_f32 v18, v20, v21
	v_cvt_pk_bf16_f32 v19, v22, v23
	global_store_dwordx4 v[14:15], v[16:19], off offset:1024
	s_waitcnt vmcnt(5)
	v_cvt_pk_bf16_f32 v26, v26, v27
	v_cvt_pk_bf16_f32 v27, v28, v29
	s_waitcnt vmcnt(4)
	v_cvt_pk_bf16_f32 v28, v30, v31
	v_cvt_pk_bf16_f32 v29, v32, v33
	global_store_dwordx4 v[42:43], v[26:29], off
	s_waitcnt vmcnt(4)
	v_cvt_pk_bf16_f32 v34, v34, v35
	v_cvt_pk_bf16_f32 v35, v36, v37
	s_waitcnt vmcnt(3)
	v_cvt_pk_bf16_f32 v36, v38, v39
	v_cvt_pk_bf16_f32 v37, v40, v41
	global_store_dwordx4 v[42:43], v[34:37], off offset:1024
	s_cbranch_scc0 .LBB0_52

.LBB0_126:
	ds_read_b128 v[130:133], v176
	ds_read_b128 v[134:137], v176 offset:1024
	ds_read_b128 v[170:173], v176 offset:2048
	ds_read_b128 v[180:183], v176 offset:3072
	ds_read_b128 v[184:187], v177
	ds_read_b128 v[188:191], v177 offset:1024
	ds_read_b128 v[192:195], v177 offset:2048
	ds_read_b128 v[198:201], v177 offset:3072
	s_add_u32 s14, s8, 0xfff00080
	s_addc_u32 s15, s9, -1
	s_cmp_eq_u32 s29, 60
	s_cselect_b32 s19, s11, s15
	s_cselect_b32 s18, s13, s14
	s_cselect_b32 s15, s17, s28
	s_cselect_b32 s14, s20, s21
	s_add_i32 m0, s73, 0xc000
	ds_read_b128 v[202:205], v178
	ds_read_b128 v[206:209], v178 offset:1024
	ds_read_b128 v[210:213], v178 offset:2048
	ds_read_b128 v[214:217], v178 offset:3072
	ds_read_b128 v[218:221], v178 offset:4096
	ds_read_b128 v[222:225], v178 offset:5120
	ds_read_b128 v[226:229], v178 offset:6144
	ds_read_b128 v[230:233], v178 offset:7168
	global_load_lds_dwordx4 v160, s[8:9]
	s_add_i32 m0, s73, 0xe000
	s_nop 0
	global_load_lds_dwordx4 v162, s[8:9]
	s_waitcnt vmcnt(8)
	s_waitcnt lgkmcnt(0)
	s_setprio 1
	s_barrier
	v_mfma_f32_16x16x32_bf16 v[126:129], v[130:133], v[202:205], v[126:129]
	v_mfma_f32_16x16x32_bf16 v[122:125], v[170:173], v[202:205], v[122:125]
	v_mfma_f32_16x16x32_bf16 v[110:113], v[130:133], v[210:213], v[110:113]
	v_mfma_f32_16x16x32_bf16 v[106:109], v[170:173], v[210:213], v[106:109]
	v_mfma_f32_16x16x32_bf16 v[94:97], v[130:133], v[218:221], v[94:97]
	v_mfma_f32_16x16x32_bf16 v[90:93], v[170:173], v[218:221], v[90:93]
	v_mfma_f32_16x16x32_bf16 v[78:81], v[130:133], v[226:229], v[78:81]
	v_mfma_f32_16x16x32_bf16 v[74:77], v[170:173], v[226:229], v[74:77]
	v_mfma_f32_16x16x32_bf16 v[126:129], v[134:137], v[206:209], v[126:129]
	v_mfma_f32_16x16x32_bf16 v[122:125], v[180:183], v[206:209], v[122:125]
	v_mfma_f32_16x16x32_bf16 v[110:113], v[134:137], v[214:217], v[110:113]
	v_mfma_f32_16x16x32_bf16 v[106:109], v[180:183], v[214:217], v[106:109]
	v_mfma_f32_16x16x32_bf16 v[94:97], v[134:137], v[222:225], v[94:97]
	v_mfma_f32_16x16x32_bf16 v[90:93], v[180:183], v[222:225], v[90:93]
	v_mfma_f32_16x16x32_bf16 v[78:81], v[134:137], v[230:233], v[78:81]
	v_mfma_f32_16x16x32_bf16 v[74:77], v[180:183], v[230:233], v[74:77]
	v_mfma_f32_16x16x32_bf16 v[118:121], v[184:187], v[202:205], v[118:121]
	v_mfma_f32_16x16x32_bf16 v[114:117], v[192:195], v[202:205], v[114:117]
	v_mfma_f32_16x16x32_bf16 v[102:105], v[184:187], v[210:213], v[102:105]
	v_mfma_f32_16x16x32_bf16 v[98:101], v[192:195], v[210:213], v[98:101]
	v_mfma_f32_16x16x32_bf16 v[86:89], v[184:187], v[218:221], v[86:89]
	v_mfma_f32_16x16x32_bf16 v[82:85], v[192:195], v[218:221], v[82:85]
	v_mfma_f32_16x16x32_bf16 v[70:73], v[184:187], v[226:229], v[70:73]
	v_mfma_f32_16x16x32_bf16 v[66:69], v[192:195], v[226:229], v[66:69]
	v_mfma_f32_16x16x32_bf16 v[118:121], v[188:191], v[206:209], v[118:121]
	v_mfma_f32_16x16x32_bf16 v[114:117], v[198:201], v[206:209], v[114:117]
	v_mfma_f32_16x16x32_bf16 v[102:105], v[188:191], v[214:217], v[102:105]
	v_mfma_f32_16x16x32_bf16 v[98:101], v[198:201], v[214:217], v[98:101]
	v_mfma_f32_16x16x32_bf16 v[86:89], v[188:191], v[222:225], v[86:89]
	v_mfma_f32_16x16x32_bf16 v[82:85], v[198:201], v[222:225], v[82:85]
	v_mfma_f32_16x16x32_bf16 v[70:73], v[188:191], v[230:233], v[70:73]
	v_mfma_f32_16x16x32_bf16 v[66:69], v[198:201], v[230:233], v[66:69]
	s_barrier
	s_setprio 0
	s_add_i32 s30, s69, s35
	s_mov_b32 m0, s30
	ds_read_b128 v[202:205], v178 offset:16384
	ds_read_b128 v[206:209], v178 offset:17408
	ds_read_b128 v[210:213], v178 offset:18432
	ds_read_b128 v[214:217], v178 offset:19456
	ds_read_b128 v[218:221], v178 offset:20480
	ds_read_b128 v[222:225], v178 offset:21504
	ds_read_b128 v[226:229], v178 offset:22528
	ds_read_b128 v[230:233], v178 offset:23552
	global_load_lds_dwordx4 v140, s[14:15]
	s_add_i32 m0, s30, 0x2000
	s_add_u32 s30, s14, 0x100000
	s_addc_u32 s31, s15, 0
	s_add_i32 s38, s70, s35
	global_load_lds_dwordx4 v144, s[14:15]
	s_mov_b32 m0, s38
	global_load_lds_dwordx4 v140, s[30:31]
	s_add_i32 m0, s38, 0x2000
	s_nop 0
	global_load_lds_dwordx4 v144, s[30:31]
	s_mov_b32 m0, s73
	s_nop 0
	global_load_lds_dwordx4 v138, s[18:19]
	s_mov_b32 m0, s66
	s_nop 0
	global_load_lds_dwordx4 v142, s[18:19]
	s_waitcnt vmcnt(8)
	s_waitcnt lgkmcnt(0)
	s_setprio 1
	s_barrier
	v_mfma_f32_16x16x32_bf16 v[62:65], v[130:133], v[202:205], v[62:65]
	v_mfma_f32_16x16x32_bf16 v[58:61], v[170:173], v[202:205], v[58:61]
	v_mfma_f32_16x16x32_bf16 v[46:49], v[130:133], v[210:213], v[46:49]
	v_mfma_f32_16x16x32_bf16 v[42:45], v[170:173], v[210:213], v[42:45]
	v_mfma_f32_16x16x32_bf16 v[30:33], v[130:133], v[218:221], v[30:33]
	v_mfma_f32_16x16x32_bf16 v[26:29], v[170:173], v[218:221], v[26:29]
	v_mfma_f32_16x16x32_bf16 v[14:17], v[130:133], v[226:229], v[14:17]
	v_mfma_f32_16x16x32_bf16 v[10:13], v[170:173], v[226:229], v[10:13]
	v_mfma_f32_16x16x32_bf16 v[62:65], v[134:137], v[206:209], v[62:65]
	v_mfma_f32_16x16x32_bf16 v[58:61], v[180:183], v[206:209], v[58:61]
	v_mfma_f32_16x16x32_bf16 v[46:49], v[134:137], v[214:217], v[46:49]
	v_mfma_f32_16x16x32_bf16 v[42:45], v[180:183], v[214:217], v[42:45]
	v_mfma_f32_16x16x32_bf16 v[30:33], v[134:137], v[222:225], v[30:33]
	v_mfma_f32_16x16x32_bf16 v[26:29], v[180:183], v[222:225], v[26:29]
	v_mfma_f32_16x16x32_bf16 v[14:17], v[134:137], v[230:233], v[14:17]
	v_mfma_f32_16x16x32_bf16 v[10:13], v[180:183], v[230:233], v[10:13]
	v_mfma_f32_16x16x32_bf16 v[54:57], v[184:187], v[202:205], v[54:57]
	v_mfma_f32_16x16x32_bf16 v[50:53], v[192:195], v[202:205], v[50:53]
	v_mfma_f32_16x16x32_bf16 v[38:41], v[184:187], v[210:213], v[38:41]
	v_mfma_f32_16x16x32_bf16 v[34:37], v[192:195], v[210:213], v[34:37]
	v_mfma_f32_16x16x32_bf16 v[22:25], v[184:187], v[218:221], v[22:25]
	v_mfma_f32_16x16x32_bf16 v[18:21], v[192:195], v[218:221], v[18:21]
	v_mfma_f32_16x16x32_bf16 v[6:9], v[184:187], v[226:229], v[6:9]
	v_mfma_f32_16x16x32_bf16 v[2:5], v[192:195], v[226:229], v[2:5]
	v_mfma_f32_16x16x32_bf16 v[54:57], v[188:191], v[206:209], v[54:57]
	v_mfma_f32_16x16x32_bf16 v[50:53], v[198:201], v[206:209], v[50:53]
	v_mfma_f32_16x16x32_bf16 v[38:41], v[188:191], v[214:217], v[38:41]
	v_mfma_f32_16x16x32_bf16 v[34:37], v[198:201], v[214:217], v[34:37]
	v_mfma_f32_16x16x32_bf16 v[22:25], v[188:191], v[222:225], v[22:25]
	v_mfma_f32_16x16x32_bf16 v[18:21], v[198:201], v[222:225], v[18:21]
	v_mfma_f32_16x16x32_bf16 v[6:9], v[188:191], v[230:233], v[6:9]
	v_mfma_f32_16x16x32_bf16 v[2:5], v[198:201], v[230:233], v[2:5]
	s_barrier
	s_setprio 0
	s_add_i32 s30, 0, 0x18000
	v_add_u32_e32 v146, s30, v155
	s_add_i32 s31, 0, 0x1c000
	ds_read_b128 v[130:133], v146
	ds_read_b128 v[134:137], v146 offset:1024
	ds_read_b128 v[170:173], v146 offset:2048
	ds_read_b128 v[180:183], v146 offset:3072
	v_add_u32_e32 v146, s31, v155
	ds_read_b128 v[184:187], v146
	ds_read_b128 v[188:191], v146 offset:1024
	ds_read_b128 v[192:195], v146 offset:2048
	ds_read_b128 v[198:201], v146 offset:3072
	s_add_u32 s18, s18, 0x100000
	s_addc_u32 s19, s19, 0
	s_mov_b32 m0, s67
	ds_read_b128 v[202:205], v178 offset:32768
	ds_read_b128 v[206:209], v178 offset:33792
	ds_read_b128 v[210:213], v178 offset:34816
	ds_read_b128 v[214:217], v178 offset:35840
	ds_read_b128 v[218:221], v178 offset:36864
	ds_read_b128 v[222:225], v178 offset:37888
	ds_read_b128 v[226:229], v178 offset:38912
	ds_read_b128 v[230:233], v178 offset:39936
	global_load_lds_dwordx4 v138, s[18:19]
	s_mov_b32 m0, s88
	s_nop 0
	global_load_lds_dwordx4 v142, s[18:19]
	s_waitcnt vmcnt(8)
	s_waitcnt lgkmcnt(0)
	s_setprio 1
	s_barrier
	v_mfma_f32_16x16x32_bf16 v[126:129], v[130:133], v[202:205], v[126:129]
	v_mfma_f32_16x16x32_bf16 v[122:125], v[170:173], v[202:205], v[122:125]
	v_mfma_f32_16x16x32_bf16 v[110:113], v[130:133], v[210:213], v[110:113]
	v_mfma_f32_16x16x32_bf16 v[106:109], v[170:173], v[210:213], v[106:109]
	v_mfma_f32_16x16x32_bf16 v[94:97], v[130:133], v[218:221], v[94:97]
	v_mfma_f32_16x16x32_bf16 v[90:93], v[170:173], v[218:221], v[90:93]
	v_mfma_f32_16x16x32_bf16 v[78:81], v[130:133], v[226:229], v[78:81]
	v_mfma_f32_16x16x32_bf16 v[74:77], v[170:173], v[226:229], v[74:77]
	v_mfma_f32_16x16x32_bf16 v[126:129], v[134:137], v[206:209], v[126:129]
	v_mfma_f32_16x16x32_bf16 v[122:125], v[180:183], v[206:209], v[122:125]
	v_mfma_f32_16x16x32_bf16 v[110:113], v[134:137], v[214:217], v[110:113]
	v_mfma_f32_16x16x32_bf16 v[106:109], v[180:183], v[214:217], v[106:109]
	v_mfma_f32_16x16x32_bf16 v[94:97], v[134:137], v[222:225], v[94:97]
	v_mfma_f32_16x16x32_bf16 v[90:93], v[180:183], v[222:225], v[90:93]
	v_mfma_f32_16x16x32_bf16 v[78:81], v[134:137], v[230:233], v[78:81]
	v_mfma_f32_16x16x32_bf16 v[74:77], v[180:183], v[230:233], v[74:77]
	v_mfma_f32_16x16x32_bf16 v[118:121], v[184:187], v[202:205], v[118:121]
	v_mfma_f32_16x16x32_bf16 v[114:117], v[192:195], v[202:205], v[114:117]
	v_mfma_f32_16x16x32_bf16 v[102:105], v[184:187], v[210:213], v[102:105]
	v_mfma_f32_16x16x32_bf16 v[98:101], v[192:195], v[210:213], v[98:101]
	v_mfma_f32_16x16x32_bf16 v[86:89], v[184:187], v[218:221], v[86:89]
	v_mfma_f32_16x16x32_bf16 v[82:85], v[192:195], v[218:221], v[82:85]
	v_mfma_f32_16x16x32_bf16 v[70:73], v[184:187], v[226:229], v[70:73]
	v_mfma_f32_16x16x32_bf16 v[66:69], v[192:195], v[226:229], v[66:69]
	v_mfma_f32_16x16x32_bf16 v[118:121], v[188:191], v[206:209], v[118:121]
	v_mfma_f32_16x16x32_bf16 v[114:117], v[198:201], v[206:209], v[114:117]
	v_mfma_f32_16x16x32_bf16 v[102:105], v[188:191], v[214:217], v[102:105]
	v_mfma_f32_16x16x32_bf16 v[98:101], v[198:201], v[214:217], v[98:101]
	v_mfma_f32_16x16x32_bf16 v[86:89], v[188:191], v[222:225], v[86:89]
	v_mfma_f32_16x16x32_bf16 v[82:85], v[198:201], v[222:225], v[82:85]
	v_mfma_f32_16x16x32_bf16 v[70:73], v[188:191], v[230:233], v[70:73]
	v_mfma_f32_16x16x32_bf16 v[66:69], v[198:201], v[230:233], v[66:69]
	s_barrier
	s_setprio 0
	s_add_u32 s14, s14, 0x80
	s_addc_u32 s15, s15, 0
	s_add_i32 m0, s35, 0x18000
	ds_read_b128 v[202:205], v178 offset:49152
	ds_read_b128 v[206:209], v178 offset:50176
	ds_read_b128 v[210:213], v178 offset:51200
	ds_read_b128 v[214:217], v178 offset:52224
	ds_read_b128 v[218:221], v178 offset:53248
	ds_read_b128 v[222:225], v178 offset:54272
	ds_read_b128 v[226:229], v178 offset:55296
	ds_read_b128 v[230:233], v178 offset:56320
	global_load_lds_dwordx4 v140, s[14:15]
	s_add_i32 m0, s35, 0x1a000
	s_add_u32 s18, s18, 0xfff00080
	global_load_lds_dwordx4 v144, s[14:15]
	s_addc_u32 s19, s19, -1
	s_add_u32 s14, s14, 0x100000
	s_addc_u32 s15, s15, 0
	s_add_i32 m0, s35, 0x1c000
	s_nop 0
	global_load_lds_dwordx4 v140, s[14:15]
	s_add_i32 m0, s35, 0x1e000
	s_nop 0
	global_load_lds_dwordx4 v144, s[14:15]
	s_mov_b32 m0, s89
	s_nop 0
	global_load_lds_dwordx4 v138, s[18:19]
	s_mov_b32 m0, s68
	s_nop 0
	global_load_lds_dwordx4 v142, s[18:19]
	s_waitcnt vmcnt(8)
	s_waitcnt lgkmcnt(0)
	s_setprio 1
	s_barrier
	v_mfma_f32_16x16x32_bf16 v[62:65], v[130:133], v[202:205], v[62:65]
	v_mfma_f32_16x16x32_bf16 v[58:61], v[170:173], v[202:205], v[58:61]
	v_mfma_f32_16x16x32_bf16 v[46:49], v[130:133], v[210:213], v[46:49]
	v_mfma_f32_16x16x32_bf16 v[42:45], v[170:173], v[210:213], v[42:45]
	v_mfma_f32_16x16x32_bf16 v[30:33], v[130:133], v[218:221], v[30:33]
	v_mfma_f32_16x16x32_bf16 v[26:29], v[170:173], v[218:221], v[26:29]
	v_mfma_f32_16x16x32_bf16 v[14:17], v[130:133], v[226:229], v[14:17]
	v_mfma_f32_16x16x32_bf16 v[10:13], v[170:173], v[226:229], v[10:13]
	v_mfma_f32_16x16x32_bf16 v[62:65], v[134:137], v[206:209], v[62:65]
	v_mfma_f32_16x16x32_bf16 v[58:61], v[180:183], v[206:209], v[58:61]
	v_mfma_f32_16x16x32_bf16 v[46:49], v[134:137], v[214:217], v[46:49]
	v_mfma_f32_16x16x32_bf16 v[42:45], v[180:183], v[214:217], v[42:45]
	v_mfma_f32_16x16x32_bf16 v[30:33], v[134:137], v[222:225], v[30:33]
	v_mfma_f32_16x16x32_bf16 v[26:29], v[180:183], v[222:225], v[26:29]
	v_mfma_f32_16x16x32_bf16 v[14:17], v[134:137], v[230:233], v[14:17]
	v_mfma_f32_16x16x32_bf16 v[10:13], v[180:183], v[230:233], v[10:13]
	v_mfma_f32_16x16x32_bf16 v[54:57], v[184:187], v[202:205], v[54:57]
	v_mfma_f32_16x16x32_bf16 v[50:53], v[192:195], v[202:205], v[50:53]
	v_mfma_f32_16x16x32_bf16 v[38:41], v[184:187], v[210:213], v[38:41]
	v_mfma_f32_16x16x32_bf16 v[34:37], v[192:195], v[210:213], v[34:37]
	v_mfma_f32_16x16x32_bf16 v[22:25], v[184:187], v[218:221], v[22:25]
	v_mfma_f32_16x16x32_bf16 v[18:21], v[192:195], v[218:221], v[18:21]
	v_mfma_f32_16x16x32_bf16 v[6:9], v[184:187], v[226:229], v[6:9]
	v_mfma_f32_16x16x32_bf16 v[2:5], v[192:195], v[226:229], v[2:5]
	v_mfma_f32_16x16x32_bf16 v[54:57], v[188:191], v[206:209], v[54:57]
	v_mfma_f32_16x16x32_bf16 v[50:53], v[198:201], v[206:209], v[50:53]
	v_mfma_f32_16x16x32_bf16 v[38:41], v[188:191], v[214:217], v[38:41]
	v_mfma_f32_16x16x32_bf16 v[34:37], v[198:201], v[214:217], v[34:37]
	v_mfma_f32_16x16x32_bf16 v[22:25], v[188:191], v[222:225], v[22:25]
	v_mfma_f32_16x16x32_bf16 v[18:21], v[198:201], v[222:225], v[18:21]
	v_mfma_f32_16x16x32_bf16 v[6:9], v[188:191], v[230:233], v[6:9]
	v_mfma_f32_16x16x32_bf16 v[2:5], v[198:201], v[230:233], v[2:5]
	s_barrier
	s_setprio 0
	s_add_i32 s29, s29, 2
	s_add_u32 s8, s8, 0x100
	s_addc_u32 s9, s9, 0
	s_add_u32 s21, s21, 0x100
	s_addc_u32 s28, s28, 0
	s_cmp_gt_u32 s29, 61
	s_cbranch_scc0 .LBB0_126
	v_readlane_b32 s8, v249, 56
	v_readlane_b32 s9, v249, 57
	s_and_b64 vcc, exec, s[8:9]
	s_cbranch_vccz .LBB0_129
	s_barrier

.LBB0_586:
	s_and_b32 s61, s60, 0x10000
	v_or_b32_e32 v2, s61, v207
	v_add_u32_e32 v6, v208, v2
	ds_read_b128 v[12:15], v6
	v_bitop3_b32 v2, s61, 32, v207 bitop3:0x36
	v_add_u32_e32 v7, v208, v2
	ds_read_b128 v[212:215], v7
	v_bitop3_b32 v2, s61, 64, v207 bitop3:0x36
	v_add_u32_e32 v8, v208, v2
	ds_read_b128 v[216:219], v8
	v_bitop3_b32 v2, s61, v199, v207 bitop3:0x36
	v_add_u32_e32 v9, v208, v2
	ds_read_b128 v[220:223], v9
	v_bitop3_b32 v2, s61, v200, v207 bitop3:0x36
	v_add_u32_e32 v10, v208, v2
	ds_read_b128 v[224:227], v10
	v_bitop3_b32 v2, s61, v201, v207 bitop3:0x36
	v_add_u32_e32 v11, v208, v2
	ds_read_b128 v[228:231], v11
	v_xor_b32_e32 v146, 0x80000000, v5
	v_mov_b32_e32 v147, v146
	v_mov_b32_e32 v148, v146
	v_mov_b32_e32 v149, v146
	v_mov_b32_e32 v150, v146
	v_mov_b32_e32 v151, v146
	v_mov_b32_e32 v152, v146
	v_mov_b32_e32 v153, v146
	v_mov_b32_e32 v154, v146
	v_mov_b32_e32 v155, v146
	v_mov_b32_e32 v156, v146
	v_mov_b32_e32 v157, v146
	v_mov_b32_e32 v158, v146
	v_mov_b32_e32 v159, v146
	v_mov_b32_e32 v160, v146
	v_mov_b32_e32 v161, v146
	s_waitcnt vmcnt(0) lgkmcnt(5)
	v_mfma_f32_32x32x16_bf16 v[146:161], v[12:15], v[162:165], v[146:161]
	v_bitop3_b32 v2, s61, v202, v207 bitop3:0x36
	v_add_u32_e32 v12, v208, v2
	ds_read_b128 v[14:17], v12
	v_bitop3_b32 v2, s61, v203, v207 bitop3:0x36
	v_add_u32_e32 v13, v208, v2
	s_cmp_lg_u32 s60, 0
	s_cselect_b64 s[42:43], -1, 0
	s_waitcnt lgkmcnt(5)
	v_mfma_f32_32x32x16_bf16 v[146:161], v[212:215], v[166:169], v[146:161]
	ds_read_b128 v[212:215], v13
	s_cmp_eq_u32 s60, 0
	s_waitcnt lgkmcnt(5)
	v_mfma_f32_32x32x16_bf16 v[146:161], v[216:219], v[170:173], v[146:161]
	ds_read_b128 v[216:219], v206
	s_waitcnt lgkmcnt(5)
	v_mfma_f32_32x32x16_bf16 v[146:161], v[220:223], v[174:177], v[146:161]
	ds_read_b128 v[220:223], v206 offset:8192
	s_waitcnt lgkmcnt(5)
	v_mfma_f32_32x32x16_bf16 v[146:161], v[224:227], v[178:181], v[146:161]
	s_waitcnt lgkmcnt(4)
	v_mfma_f32_32x32x16_bf16 v[146:161], v[228:231], v[182:185], v[146:161]
	s_waitcnt lgkmcnt(1)
	v_mfma_f32_32x32x16_bf16 v[146:161], v[14:17], v[216:219], v[146:161]
	s_waitcnt lgkmcnt(0)
	v_mfma_f32_32x32x16_bf16 v[146:161], v[212:215], v[220:223], v[146:161]
	s_nop 11
	v_max_f32_e32 v2, v147, v147
	v_max_f32_e32 v4, v146, v146
	v_max_f32_e32 v2, v4, v2
	v_max3_f32 v2, v2, v148, v149
	v_max3_f32 v2, v2, v150, v151
	v_max3_f32 v2, v2, v152, v153
	v_max3_f32 v2, v2, v154, v155
	v_max3_f32 v2, v2, v156, v157
	v_max3_f32 v2, v2, v158, v159
	v_max3_f32 v2, v2, v160, v161
	v_mov_b32_e32 v4, v2
	s_nop 1
	v_permlane32_swap_b32_e32 v2, v4
	s_cbranch_scc1 .LBB0_589
	v_cmp_lt_f32_e32 vcc, s84, v2
	s_cbranch_vccz .LBB0_590
	v_max_f32_e32 v2, v2, v2
	v_max_f32_e32 v2, 0, v2

.LBB0_598:
	ds_read_b128 v[224:227], v6 offset:16384
	ds_read_b128 v[228:231], v7 offset:16384
	ds_read_b128 v[232:235], v8 offset:16384
	ds_read_b128 v[6:9], v9 offset:16384
	ds_read_b128 v[236:239], v10 offset:16384
	ds_read_b128 v[240:243], v11 offset:16384
	v_xor_b32_e32 v146, 0x80000000, v5
	v_mov_b32_e32 v147, v146
	v_mov_b32_e32 v148, v146
	v_mov_b32_e32 v149, v146
	v_mov_b32_e32 v150, v146
	v_mov_b32_e32 v151, v146
	v_mov_b32_e32 v152, v146
	v_mov_b32_e32 v153, v146
	v_mov_b32_e32 v154, v146
	v_mov_b32_e32 v155, v146
	v_mov_b32_e32 v156, v146
	v_mov_b32_e32 v157, v146
	v_mov_b32_e32 v158, v146
	v_mov_b32_e32 v159, v146
	v_mov_b32_e32 v160, v146
	v_mov_b32_e32 v161, v146
	s_waitcnt lgkmcnt(5)
	v_mfma_f32_32x32x16_bf16 v[146:161], v[224:227], v[162:165], v[146:161]
	ds_read_b128 v[224:227], v12 offset:16384
	v_add_f32_e32 v2, v2, v4
	v_add_f32_e32 v4, v16, v15
	v_add_f32_e32 v2, 0, v2
	v_add_f32_e32 v15, v212, v17
	v_add_f32_e32 v2, v4, v2
	v_add_f32_e32 v16, v214, v213
	s_waitcnt lgkmcnt(5)
	v_mfma_f32_32x32x16_bf16 v[146:161], v[228:231], v[166:169], v[146:161]
	ds_read_b128 v[10:13], v13 offset:16384
	v_add_f32_e32 v2, v15, v2
	v_add_f32_e32 v17, v216, v215
	v_add_f32_e32 v2, v16, v2
	v_add_f32_e32 v212, v218, v217
	v_add_f32_e32 v2, v17, v2
	v_add_f32_e32 v213, v220, v219
	s_waitcnt lgkmcnt(5)
	v_mfma_f32_32x32x16_bf16 v[146:161], v[232:235], v[170:173], v[146:161]
	ds_read_b128 v[228:231], v206
	v_add_f32_e32 v2, v212, v2
	v_add_f32_e32 v214, v221, v222
	v_add_f32_e32 v2, v213, v2
	v_add_f32_e32 v2, v214, v2
	s_waitcnt lgkmcnt(5)
	v_mfma_f32_32x32x16_bf16 v[146:161], v[6:9], v[174:177], v[146:161]
	ds_read_b128 v[6:9], v206 offset:8192
	s_waitcnt lgkmcnt(5)
	v_mfma_f32_32x32x16_bf16 v[146:161], v[236:239], v[178:181], v[146:161]
	s_waitcnt lgkmcnt(4)
	v_mfma_f32_32x32x16_bf16 v[146:161], v[240:243], v[182:185], v[146:161]
	s_waitcnt lgkmcnt(0)
	v_mfma_f32_32x32x16_bf16 v[146:161], v[224:227], v[228:231], v[146:161]
	v_mfma_f32_32x32x16_bf16 v[146:161], v[10:13], v[6:9], v[146:161]
	v_add_f32_e32 v6, v211, v2
	s_nop 10
	v_max_f32_e32 v2, v147, v147
	v_max_f32_e32 v4, v146, v146
	v_max_f32_e32 v2, v4, v2
	v_max3_f32 v2, v2, v148, v149
	v_max3_f32 v2, v2, v150, v151
	v_max3_f32 v2, v2, v152, v153
	v_max3_f32 v2, v2, v154, v155
	v_max3_f32 v2, v2, v156, v157
	v_max3_f32 v2, v2, v158, v159
	v_max3_f32 v2, v2, v160, v161
	v_mov_b32_e32 v4, v2
	s_nop 1
	v_permlane32_swap_b32_e32 v2, v4
	v_cmp_lt_f32_e32 vcc, s84, v2
	s_cbranch_vccz .LBB0_600
	v_max_f32_e32 v2, v2, v2
	v_max_f32_e32 v2, 0, v2
	v_exp_f32_e64 v4, -v2
	v_pk_add_f32 v[146:147], v[146:147], v[2:3] op_sel_hi:[1,0] neg_lo:[0,1] neg_hi:[0,1]
	v_pk_add_f32 v[148:149], v[148:149], v[2:3] op_sel_hi:[1,0] neg_lo:[0,1] neg_hi:[0,1]
	v_pk_add_f32 v[150:151], v[150:151], v[2:3] op_sel_hi:[1,0] neg_lo:[0,1] neg_hi:[0,1]
	v_mul_f32_e32 v6, v6, v4
	v_pk_mul_f32 v[32:33], v[32:33], v[4:5] op_sel_hi:[1,0]
	v_pk_mul_f32 v[30:31], v[30:31], v[4:5] op_sel_hi:[1,0]
	v_pk_mul_f32 v[28:29], v[28:29], v[4:5] op_sel_hi:[1,0]
	v_pk_mul_f32 v[26:27], v[26:27], v[4:5] op_sel_hi:[1,0]
	v_pk_mul_f32 v[24:25], v[24:25], v[4:5] op_sel_hi:[1,0]
	v_pk_mul_f32 v[22:23], v[22:23], v[4:5] op_sel_hi:[1,0]
	v_pk_mul_f32 v[20:21], v[20:21], v[4:5] op_sel_hi:[1,0]
	v_pk_mul_f32 v[18:19], v[18:19], v[4:5] op_sel_hi:[1,0]
	v_pk_mul_f32 v[48:49], v[48:49], v[4:5] op_sel_hi:[1,0]
	v_pk_mul_f32 v[46:47], v[46:47], v[4:5] op_sel_hi:[1,0]
	v_pk_mul_f32 v[44:45], v[44:45], v[4:5] op_sel_hi:[1,0]
	v_pk_mul_f32 v[42:43], v[42:43], v[4:5] op_sel_hi:[1,0]
	v_pk_mul_f32 v[40:41], v[40:41], v[4:5] op_sel_hi:[1,0]
	v_pk_mul_f32 v[38:39], v[38:39], v[4:5] op_sel_hi:[1,0]
	v_pk_mul_f32 v[36:37], v[36:37], v[4:5] op_sel_hi:[1,0]
	v_pk_mul_f32 v[34:35], v[34:35], v[4:5] op_sel_hi:[1,0]
	v_pk_mul_f32 v[64:65], v[64:65], v[4:5] op_sel_hi:[1,0]
	v_pk_mul_f32 v[62:63], v[62:63], v[4:5] op_sel_hi:[1,0]
	v_pk_mul_f32 v[60:61], v[60:61], v[4:5] op_sel_hi:[1,0]
	v_pk_mul_f32 v[58:59], v[58:59], v[4:5] op_sel_hi:[1,0]
	v_pk_mul_f32 v[56:57], v[56:57], v[4:5] op_sel_hi:[1,0]
	v_pk_mul_f32 v[54:55], v[54:55], v[4:5] op_sel_hi:[1,0]
	v_pk_mul_f32 v[52:53], v[52:53], v[4:5] op_sel_hi:[1,0]
	v_pk_mul_f32 v[50:51], v[50:51], v[4:5] op_sel_hi:[1,0]
	v_pk_mul_f32 v[80:81], v[80:81], v[4:5] op_sel_hi:[1,0]
	v_pk_mul_f32 v[78:79], v[78:79], v[4:5] op_sel_hi:[1,0]
	v_pk_mul_f32 v[76:77], v[76:77], v[4:5] op_sel_hi:[1,0]
	v_pk_mul_f32 v[74:75], v[74:75], v[4:5] op_sel_hi:[1,0]
	v_pk_mul_f32 v[72:73], v[72:73], v[4:5] op_sel_hi:[1,0]
	v_pk_mul_f32 v[70:71], v[70:71], v[4:5] op_sel_hi:[1,0]
	v_pk_mul_f32 v[68:69], v[68:69], v[4:5] op_sel_hi:[1,0]
	v_pk_mul_f32 v[66:67], v[66:67], v[4:5] op_sel_hi:[1,0]
	v_pk_mul_f32 v[96:97], v[96:97], v[4:5] op_sel_hi:[1,0]
	v_pk_mul_f32 v[94:95], v[94:95], v[4:5] op_sel_hi:[1,0]
	v_pk_mul_f32 v[92:93], v[92:93], v[4:5] op_sel_hi:[1,0]
	v_pk_mul_f32 v[90:91], v[90:91], v[4:5] op_sel_hi:[1,0]
	v_pk_mul_f32 v[88:89], v[88:89], v[4:5] op_sel_hi:[1,0]
	v_pk_mul_f32 v[86:87], v[86:87], v[4:5] op_sel_hi:[1,0]
	v_pk_mul_f32 v[84:85], v[84:85], v[4:5] op_sel_hi:[1,0]
	v_pk_mul_f32 v[82:83], v[82:83], v[4:5] op_sel_hi:[1,0]
	v_pk_mul_f32 v[112:113], v[112:113], v[4:5] op_sel_hi:[1,0]
	v_pk_mul_f32 v[110:111], v[110:111], v[4:5] op_sel_hi:[1,0]
	v_pk_mul_f32 v[108:109], v[108:109], v[4:5] op_sel_hi:[1,0]
	v_pk_mul_f32 v[106:107], v[106:107], v[4:5] op_sel_hi:[1,0]
	v_pk_mul_f32 v[104:105], v[104:105], v[4:5] op_sel_hi:[1,0]
	v_pk_mul_f32 v[102:103], v[102:103], v[4:5] op_sel_hi:[1,0]
	v_pk_mul_f32 v[100:101], v[100:101], v[4:5] op_sel_hi:[1,0]
	v_pk_mul_f32 v[98:99], v[98:99], v[4:5] op_sel_hi:[1,0]
	v_pk_mul_f32 v[128:129], v[128:129], v[4:5] op_sel_hi:[1,0]
	v_pk_mul_f32 v[126:127], v[126:127], v[4:5] op_sel_hi:[1,0]
	v_pk_mul_f32 v[124:125], v[124:125], v[4:5] op_sel_hi:[1,0]
	v_pk_mul_f32 v[122:123], v[122:123], v[4:5] op_sel_hi:[1,0]
	v_pk_mul_f32 v[120:121], v[120:121], v[4:5] op_sel_hi:[1,0]
	v_pk_mul_f32 v[118:119], v[118:119], v[4:5] op_sel_hi:[1,0]
	v_pk_mul_f32 v[116:117], v[116:117], v[4:5] op_sel_hi:[1,0]
	v_pk_mul_f32 v[114:115], v[114:115], v[4:5] op_sel_hi:[1,0]
	v_pk_mul_f32 v[144:145], v[144:145], v[4:5] op_sel_hi:[1,0]
	v_pk_mul_f32 v[142:143], v[142:143], v[4:5] op_sel_hi:[1,0]
	v_pk_mul_f32 v[140:141], v[140:141], v[4:5] op_sel_hi:[1,0]
	v_pk_mul_f32 v[138:139], v[138:139], v[4:5] op_sel_hi:[1,0]
	v_pk_mul_f32 v[136:137], v[136:137], v[4:5] op_sel_hi:[1,0]
	v_pk_mul_f32 v[134:135], v[134:135], v[4:5] op_sel_hi:[1,0]
	v_pk_mul_f32 v[132:133], v[132:133], v[4:5] op_sel_hi:[1,0]
	v_pk_mul_f32 v[130:131], v[130:131], v[4:5] op_sel_hi:[1,0]
	v_pk_add_f32 v[152:153], v[152:153], v[2:3] op_sel_hi:[1,0] neg_lo:[0,1] neg_hi:[0,1]
	v_pk_add_f32 v[154:155], v[154:155], v[2:3] op_sel_hi:[1,0] neg_lo:[0,1] neg_hi:[0,1]
	v_pk_add_f32 v[156:157], v[156:157], v[2:3] op_sel_hi:[1,0] neg_lo:[0,1] neg_hi:[0,1]
	v_pk_add_f32 v[158:159], v[158:159], v[2:3] op_sel_hi:[1,0] neg_lo:[0,1] neg_hi:[0,1]
	v_pk_add_f32 v[160:161], v[160:161], v[2:3] op_sel_hi:[1,0] neg_lo:[0,1] neg_hi:[0,1]
	v_add_f32_e32 v5, v5, v2

.LBB0_678:
	ds_read_b128 v[148:151], v159
	ds_read_b128 v[152:155], v159 offset:1024
	ds_read_b128 v[164:167], v159 offset:2048
	ds_read_b128 v[168:171], v159 offset:3072
	ds_read_b128 v[172:175], v160
	ds_read_b128 v[176:179], v160 offset:1024
	ds_read_b128 v[180:183], v160 offset:2048
	ds_read_b128 v[184:187], v160 offset:3072
	s_add_u32 s60, s58, 0xfff00080
	s_addc_u32 s61, s59, -1
	s_cmp_eq_u32 s78, 60
	s_cselect_b32 s63, s7, s61
	s_cselect_b32 s62, s47, s60
	s_cselect_b32 s61, s45, s77
	s_cselect_b32 s60, s57, s76
	s_add_i32 m0, s64, 0xc000
	ds_read_b128 v[188:191], v161
	ds_read_b128 v[192:195], v161 offset:1024
	ds_read_b128 v[198:201], v161 offset:2048
	ds_read_b128 v[202:205], v161 offset:3072
	ds_read_b128 v[206:209], v161 offset:4096
	ds_read_b128 v[210:213], v161 offset:5120
	ds_read_b128 v[214:217], v161 offset:6144
	ds_read_b128 v[218:221], v161 offset:7168
	global_load_lds_dwordx4 v140, s[58:59]
	s_add_i32 m0, s64, 0xe000
	s_nop 0
	global_load_lds_dwordx4 v142, s[58:59]
	s_waitcnt vmcnt(8)
	s_waitcnt lgkmcnt(0)
	s_setprio 1
	s_barrier
	v_mfma_f32_16x16x32_bf16 v[126:129], v[148:151], v[188:191], v[126:129]
	v_mfma_f32_16x16x32_bf16 v[122:125], v[164:167], v[188:191], v[122:125]
	v_mfma_f32_16x16x32_bf16 v[110:113], v[148:151], v[198:201], v[110:113]
	v_mfma_f32_16x16x32_bf16 v[106:109], v[164:167], v[198:201], v[106:109]
	v_mfma_f32_16x16x32_bf16 v[94:97], v[148:151], v[206:209], v[94:97]
	v_mfma_f32_16x16x32_bf16 v[90:93], v[164:167], v[206:209], v[90:93]
	v_mfma_f32_16x16x32_bf16 v[78:81], v[148:151], v[214:217], v[78:81]
	v_mfma_f32_16x16x32_bf16 v[74:77], v[164:167], v[214:217], v[74:77]
	v_mfma_f32_16x16x32_bf16 v[126:129], v[152:155], v[192:195], v[126:129]
	v_mfma_f32_16x16x32_bf16 v[122:125], v[168:171], v[192:195], v[122:125]
	v_mfma_f32_16x16x32_bf16 v[110:113], v[152:155], v[202:205], v[110:113]
	v_mfma_f32_16x16x32_bf16 v[106:109], v[168:171], v[202:205], v[106:109]
	v_mfma_f32_16x16x32_bf16 v[94:97], v[152:155], v[210:213], v[94:97]
	v_mfma_f32_16x16x32_bf16 v[90:93], v[168:171], v[210:213], v[90:93]
	v_mfma_f32_16x16x32_bf16 v[78:81], v[152:155], v[218:221], v[78:81]
	v_mfma_f32_16x16x32_bf16 v[74:77], v[168:171], v[218:221], v[74:77]
	v_mfma_f32_16x16x32_bf16 v[118:121], v[172:175], v[188:191], v[118:121]
	v_mfma_f32_16x16x32_bf16 v[114:117], v[180:183], v[188:191], v[114:117]
	v_mfma_f32_16x16x32_bf16 v[102:105], v[172:175], v[198:201], v[102:105]
	v_mfma_f32_16x16x32_bf16 v[98:101], v[180:183], v[198:201], v[98:101]
	v_mfma_f32_16x16x32_bf16 v[86:89], v[172:175], v[206:209], v[86:89]
	v_mfma_f32_16x16x32_bf16 v[82:85], v[180:183], v[206:209], v[82:85]
	v_mfma_f32_16x16x32_bf16 v[70:73], v[172:175], v[214:217], v[70:73]
	v_mfma_f32_16x16x32_bf16 v[66:69], v[180:183], v[214:217], v[66:69]
	v_mfma_f32_16x16x32_bf16 v[118:121], v[176:179], v[192:195], v[118:121]
	v_mfma_f32_16x16x32_bf16 v[114:117], v[184:187], v[192:195], v[114:117]
	v_mfma_f32_16x16x32_bf16 v[102:105], v[176:179], v[202:205], v[102:105]
	v_mfma_f32_16x16x32_bf16 v[98:101], v[184:187], v[202:205], v[98:101]
	v_mfma_f32_16x16x32_bf16 v[86:89], v[176:179], v[210:213], v[86:89]
	v_mfma_f32_16x16x32_bf16 v[82:85], v[184:187], v[210:213], v[82:85]
	v_mfma_f32_16x16x32_bf16 v[70:73], v[176:179], v[218:221], v[70:73]
	v_mfma_f32_16x16x32_bf16 v[66:69], v[184:187], v[218:221], v[66:69]
	s_barrier
	s_setprio 0
	s_add_i32 s79, s74, s33
	s_mov_b32 m0, s79
	ds_read_b128 v[188:191], v161 offset:16384
	ds_read_b128 v[192:195], v161 offset:17408
	ds_read_b128 v[198:201], v161 offset:18432
	ds_read_b128 v[202:205], v161 offset:19456
	ds_read_b128 v[206:209], v161 offset:20480
	ds_read_b128 v[210:213], v161 offset:21504
	ds_read_b128 v[214:217], v161 offset:22528
	ds_read_b128 v[218:221], v161 offset:23552
	global_load_lds_dwordx4 v132, s[60:61]
	s_add_i32 m0, s79, 0x2000
	s_add_u32 s80, s60, 0x100000
	s_addc_u32 s81, s61, 0
	s_add_i32 s79, s75, s33
	global_load_lds_dwordx4 v136, s[60:61]
	s_mov_b32 m0, s79
	global_load_lds_dwordx4 v132, s[80:81]
	s_add_i32 m0, s79, 0x2000
	s_nop 0
	global_load_lds_dwordx4 v136, s[80:81]
	s_mov_b32 m0, s64
	s_nop 0
	global_load_lds_dwordx4 v130, s[62:63]
	s_mov_b32 m0, s65
	s_nop 0
	global_load_lds_dwordx4 v134, s[62:63]
	s_waitcnt vmcnt(8)
	s_waitcnt lgkmcnt(0)
	s_setprio 1
	s_barrier
	v_mfma_f32_16x16x32_bf16 v[62:65], v[148:151], v[188:191], v[62:65]
	v_mfma_f32_16x16x32_bf16 v[58:61], v[164:167], v[188:191], v[58:61]
	v_mfma_f32_16x16x32_bf16 v[46:49], v[148:151], v[198:201], v[46:49]
	v_mfma_f32_16x16x32_bf16 v[42:45], v[164:167], v[198:201], v[42:45]
	v_mfma_f32_16x16x32_bf16 v[30:33], v[148:151], v[206:209], v[30:33]
	v_mfma_f32_16x16x32_bf16 v[26:29], v[164:167], v[206:209], v[26:29]
	v_mfma_f32_16x16x32_bf16 v[14:17], v[148:151], v[214:217], v[14:17]
	v_mfma_f32_16x16x32_bf16 v[10:13], v[164:167], v[214:217], v[10:13]
	v_mfma_f32_16x16x32_bf16 v[62:65], v[152:155], v[192:195], v[62:65]
	v_mfma_f32_16x16x32_bf16 v[58:61], v[168:171], v[192:195], v[58:61]
	v_mfma_f32_16x16x32_bf16 v[46:49], v[152:155], v[202:205], v[46:49]
	v_mfma_f32_16x16x32_bf16 v[42:45], v[168:171], v[202:205], v[42:45]
	v_mfma_f32_16x16x32_bf16 v[30:33], v[152:155], v[210:213], v[30:33]
	v_mfma_f32_16x16x32_bf16 v[26:29], v[168:171], v[210:213], v[26:29]
	v_mfma_f32_16x16x32_bf16 v[14:17], v[152:155], v[218:221], v[14:17]
	v_mfma_f32_16x16x32_bf16 v[10:13], v[168:171], v[218:221], v[10:13]
	v_mfma_f32_16x16x32_bf16 v[54:57], v[172:175], v[188:191], v[54:57]
	v_mfma_f32_16x16x32_bf16 v[50:53], v[180:183], v[188:191], v[50:53]
	v_mfma_f32_16x16x32_bf16 v[38:41], v[172:175], v[198:201], v[38:41]
	v_mfma_f32_16x16x32_bf16 v[34:37], v[180:183], v[198:201], v[34:37]
	v_mfma_f32_16x16x32_bf16 v[22:25], v[172:175], v[206:209], v[22:25]
	v_mfma_f32_16x16x32_bf16 v[18:21], v[180:183], v[206:209], v[18:21]
	v_mfma_f32_16x16x32_bf16 v[6:9], v[172:175], v[214:217], v[6:9]
	v_mfma_f32_16x16x32_bf16 v[2:5], v[180:183], v[214:217], v[2:5]
	v_mfma_f32_16x16x32_bf16 v[54:57], v[176:179], v[192:195], v[54:57]
	v_mfma_f32_16x16x32_bf16 v[50:53], v[184:187], v[192:195], v[50:53]
	v_mfma_f32_16x16x32_bf16 v[38:41], v[176:179], v[202:205], v[38:41]
	v_mfma_f32_16x16x32_bf16 v[34:37], v[184:187], v[202:205], v[34:37]
	v_mfma_f32_16x16x32_bf16 v[22:25], v[176:179], v[210:213], v[22:25]
	v_mfma_f32_16x16x32_bf16 v[18:21], v[184:187], v[210:213], v[18:21]
	v_mfma_f32_16x16x32_bf16 v[6:9], v[176:179], v[218:221], v[6:9]
	v_mfma_f32_16x16x32_bf16 v[2:5], v[184:187], v[218:221], v[2:5]
	s_barrier
	s_setprio 0
	s_add_i32 s79, 0, 0x18000
	v_add_u32_e32 v138, s79, v157
	s_add_i32 s80, 0, 0x1c000
	ds_read_b128 v[148:151], v138
	ds_read_b128 v[152:155], v138 offset:1024
	ds_read_b128 v[164:167], v138 offset:2048
	ds_read_b128 v[168:171], v138 offset:3072
	v_add_u32_e32 v138, s80, v157
	ds_read_b128 v[172:175], v138
	ds_read_b128 v[176:179], v138 offset:1024
	ds_read_b128 v[180:183], v138 offset:2048
	ds_read_b128 v[184:187], v138 offset:3072
	s_add_u32 s62, s62, 0x100000
	s_addc_u32 s63, s63, 0
	s_mov_b32 m0, s66
	ds_read_b128 v[188:191], v161 offset:32768
	ds_read_b128 v[192:195], v161 offset:33792
	ds_read_b128 v[198:201], v161 offset:34816
	ds_read_b128 v[202:205], v161 offset:35840
	ds_read_b128 v[206:209], v161 offset:36864
	ds_read_b128 v[210:213], v161 offset:37888
	ds_read_b128 v[214:217], v161 offset:38912
	ds_read_b128 v[218:221], v161 offset:39936
	global_load_lds_dwordx4 v130, s[62:63]
	s_mov_b32 m0, s67
	s_nop 0
	global_load_lds_dwordx4 v134, s[62:63]
	s_waitcnt vmcnt(8)
	s_waitcnt lgkmcnt(0)
	s_setprio 1
	s_barrier
	v_mfma_f32_16x16x32_bf16 v[126:129], v[148:151], v[188:191], v[126:129]
	v_mfma_f32_16x16x32_bf16 v[122:125], v[164:167], v[188:191], v[122:125]
	v_mfma_f32_16x16x32_bf16 v[110:113], v[148:151], v[198:201], v[110:113]
	v_mfma_f32_16x16x32_bf16 v[106:109], v[164:167], v[198:201], v[106:109]
	v_mfma_f32_16x16x32_bf16 v[94:97], v[148:151], v[206:209], v[94:97]
	v_mfma_f32_16x16x32_bf16 v[90:93], v[164:167], v[206:209], v[90:93]
	v_mfma_f32_16x16x32_bf16 v[78:81], v[148:151], v[214:217], v[78:81]
	v_mfma_f32_16x16x32_bf16 v[74:77], v[164:167], v[214:217], v[74:77]
	v_mfma_f32_16x16x32_bf16 v[126:129], v[152:155], v[192:195], v[126:129]
	v_mfma_f32_16x16x32_bf16 v[122:125], v[168:171], v[192:195], v[122:125]
	v_mfma_f32_16x16x32_bf16 v[110:113], v[152:155], v[202:205], v[110:113]
	v_mfma_f32_16x16x32_bf16 v[106:109], v[168:171], v[202:205], v[106:109]
	v_mfma_f32_16x16x32_bf16 v[94:97], v[152:155], v[210:213], v[94:97]
	v_mfma_f32_16x16x32_bf16 v[90:93], v[168:171], v[210:213], v[90:93]
	v_mfma_f32_16x16x32_bf16 v[78:81], v[152:155], v[218:221], v[78:81]
	v_mfma_f32_16x16x32_bf16 v[74:77], v[168:171], v[218:221], v[74:77]
	v_mfma_f32_16x16x32_bf16 v[118:121], v[172:175], v[188:191], v[118:121]
	v_mfma_f32_16x16x32_bf16 v[114:117], v[180:183], v[188:191], v[114:117]
	v_mfma_f32_16x16x32_bf16 v[102:105], v[172:175], v[198:201], v[102:105]
	v_mfma_f32_16x16x32_bf16 v[98:101], v[180:183], v[198:201], v[98:101]
	v_mfma_f32_16x16x32_bf16 v[86:89], v[172:175], v[206:209], v[86:89]
	v_mfma_f32_16x16x32_bf16 v[82:85], v[180:183], v[206:209], v[82:85]
	v_mfma_f32_16x16x32_bf16 v[70:73], v[172:175], v[214:217], v[70:73]
	v_mfma_f32_16x16x32_bf16 v[66:69], v[180:183], v[214:217], v[66:69]
	v_mfma_f32_16x16x32_bf16 v[118:121], v[176:179], v[192:195], v[118:121]
	v_mfma_f32_16x16x32_bf16 v[114:117], v[184:187], v[192:195], v[114:117]
	v_mfma_f32_16x16x32_bf16 v[102:105], v[176:179], v[202:205], v[102:105]
	v_mfma_f32_16x16x32_bf16 v[98:101], v[184:187], v[202:205], v[98:101]
	v_mfma_f32_16x16x32_bf16 v[86:89], v[176:179], v[210:213], v[86:89]
	v_mfma_f32_16x16x32_bf16 v[82:85], v[184:187], v[210:213], v[82:85]
	v_mfma_f32_16x16x32_bf16 v[70:73], v[176:179], v[218:221], v[70:73]
	v_mfma_f32_16x16x32_bf16 v[66:69], v[184:187], v[218:221], v[66:69]
	s_barrier
	s_setprio 0
	s_add_u32 s60, s60, 0x80
	s_addc_u32 s61, s61, 0
	s_add_i32 m0, s33, 0x18000
	ds_read_b128 v[188:191], v161 offset:49152
	ds_read_b128 v[192:195], v161 offset:50176
	ds_read_b128 v[198:201], v161 offset:51200
	ds_read_b128 v[202:205], v161 offset:52224
	ds_read_b128 v[206:209], v161 offset:53248
	ds_read_b128 v[210:213], v161 offset:54272
	ds_read_b128 v[214:217], v161 offset:55296
	ds_read_b128 v[218:221], v161 offset:56320
	global_load_lds_dwordx4 v132, s[60:61]
	s_add_i32 m0, s33, 0x1a000
	s_add_u32 s62, s62, 0xfff00080
	global_load_lds_dwordx4 v136, s[60:61]
	s_addc_u32 s63, s63, -1
	s_add_u32 s60, s60, 0x100000
	s_addc_u32 s61, s61, 0
	s_add_i32 m0, s33, 0x1c000
	s_nop 0
	global_load_lds_dwordx4 v132, s[60:61]
	s_add_i32 m0, s33, 0x1e000
	s_nop 0
	global_load_lds_dwordx4 v136, s[60:61]
	s_mov_b32 m0, s69
	s_nop 0
	global_load_lds_dwordx4 v130, s[62:63]
	s_mov_b32 m0, s70
	s_nop 0
	global_load_lds_dwordx4 v134, s[62:63]
	s_waitcnt vmcnt(8)
	s_waitcnt lgkmcnt(0)
	s_setprio 1
	s_barrier
	v_mfma_f32_16x16x32_bf16 v[62:65], v[148:151], v[188:191], v[62:65]
	v_mfma_f32_16x16x32_bf16 v[58:61], v[164:167], v[188:191], v[58:61]
	v_mfma_f32_16x16x32_bf16 v[46:49], v[148:151], v[198:201], v[46:49]
	v_mfma_f32_16x16x32_bf16 v[42:45], v[164:167], v[198:201], v[42:45]
	v_mfma_f32_16x16x32_bf16 v[30:33], v[148:151], v[206:209], v[30:33]
	v_mfma_f32_16x16x32_bf16 v[26:29], v[164:167], v[206:209], v[26:29]
	v_mfma_f32_16x16x32_bf16 v[14:17], v[148:151], v[214:217], v[14:17]
	v_mfma_f32_16x16x32_bf16 v[10:13], v[164:167], v[214:217], v[10:13]
	v_mfma_f32_16x16x32_bf16 v[62:65], v[152:155], v[192:195], v[62:65]
	v_mfma_f32_16x16x32_bf16 v[58:61], v[168:171], v[192:195], v[58:61]
	v_mfma_f32_16x16x32_bf16 v[46:49], v[152:155], v[202:205], v[46:49]
	v_mfma_f32_16x16x32_bf16 v[42:45], v[168:171], v[202:205], v[42:45]
	v_mfma_f32_16x16x32_bf16 v[30:33], v[152:155], v[210:213], v[30:33]
	v_mfma_f32_16x16x32_bf16 v[26:29], v[168:171], v[210:213], v[26:29]
	v_mfma_f32_16x16x32_bf16 v[14:17], v[152:155], v[218:221], v[14:17]
	v_mfma_f32_16x16x32_bf16 v[10:13], v[168:171], v[218:221], v[10:13]
	v_mfma_f32_16x16x32_bf16 v[54:57], v[172:175], v[188:191], v[54:57]
	v_mfma_f32_16x16x32_bf16 v[50:53], v[180:183], v[188:191], v[50:53]
	v_mfma_f32_16x16x32_bf16 v[38:41], v[172:175], v[198:201], v[38:41]
	v_mfma_f32_16x16x32_bf16 v[34:37], v[180:183], v[198:201], v[34:37]
	v_mfma_f32_16x16x32_bf16 v[22:25], v[172:175], v[206:209], v[22:25]
	v_mfma_f32_16x16x32_bf16 v[18:21], v[180:183], v[206:209], v[18:21]
	v_mfma_f32_16x16x32_bf16 v[6:9], v[172:175], v[214:217], v[6:9]
	v_mfma_f32_16x16x32_bf16 v[2:5], v[180:183], v[214:217], v[2:5]
	v_mfma_f32_16x16x32_bf16 v[54:57], v[176:179], v[192:195], v[54:57]
	v_mfma_f32_16x16x32_bf16 v[50:53], v[184:187], v[192:195], v[50:53]
	v_mfma_f32_16x16x32_bf16 v[38:41], v[176:179], v[202:205], v[38:41]
	v_mfma_f32_16x16x32_bf16 v[34:37], v[184:187], v[202:205], v[34:37]
	v_mfma_f32_16x16x32_bf16 v[22:25], v[176:179], v[210:213], v[22:25]
	v_mfma_f32_16x16x32_bf16 v[18:21], v[184:187], v[210:213], v[18:21]
	v_mfma_f32_16x16x32_bf16 v[6:9], v[176:179], v[218:221], v[6:9]
	v_mfma_f32_16x16x32_bf16 v[2:5], v[184:187], v[218:221], v[2:5]
	s_barrier
	s_setprio 0
	s_add_i32 s78, s78, 2
	s_add_u32 s58, s58, 0x100
	s_addc_u32 s59, s59, 0
	s_add_u32 s76, s76, 0x100
	s_addc_u32 s77, s77, 0
	s_cmp_gt_u32 s78, 61
	s_cbranch_scc0 .LBB0_678
	s_and_b64 vcc, exec, s[18:19]
	s_cbranch_vccz .LBB0_681
	s_barrier

.LBB0_807:
	ds_read_b128 v[154:157], v150
	ds_read_b128 v[158:161], v150 offset:1024
	ds_read_b128 v[162:165], v150 offset:2048
	ds_read_b128 v[166:169], v150 offset:3072
	ds_read_b128 v[170:173], v151
	ds_read_b128 v[174:177], v151 offset:1024
	ds_read_b128 v[178:181], v151 offset:2048
	ds_read_b128 v[182:185], v151 offset:3072
	s_add_u32 s44, s42, 0xfff00080
	s_addc_u32 s45, s43, -1
	s_cmp_eq_u32 s68, 60
	s_cselect_b32 s47, s35, s45
	s_cselect_b32 s46, s64, s44
	s_cselect_b32 s45, s31, s67
	s_cselect_b32 s44, s65, s66
	s_add_i32 m0, s41, 0xc000
	ds_read_b128 v[186:189], v152
	ds_read_b128 v[190:193], v152 offset:1024
	ds_read_b128 v[198:201], v152 offset:2048
	ds_read_b128 v[202:205], v152 offset:3072
	ds_read_b128 v[206:209], v152 offset:4096
	ds_read_b128 v[210:213], v152 offset:5120
	ds_read_b128 v[214:217], v152 offset:6144
	ds_read_b128 v[218:221], v152 offset:7168
	global_load_lds_dwordx4 v138, s[42:43]
	s_add_i32 m0, s41, 0xe000
	s_nop 0
	global_load_lds_dwordx4 v140, s[42:43]
	s_waitcnt vmcnt(8)
	s_waitcnt lgkmcnt(0)
	s_setprio 1
	s_barrier
	v_mfma_f32_16x16x32_bf16 v[126:129], v[154:157], v[186:189], v[126:129]
	v_mfma_f32_16x16x32_bf16 v[122:125], v[162:165], v[186:189], v[122:125]
	v_mfma_f32_16x16x32_bf16 v[110:113], v[154:157], v[198:201], v[110:113]
	v_mfma_f32_16x16x32_bf16 v[106:109], v[162:165], v[198:201], v[106:109]
	v_mfma_f32_16x16x32_bf16 v[94:97], v[154:157], v[206:209], v[94:97]
	v_mfma_f32_16x16x32_bf16 v[90:93], v[162:165], v[206:209], v[90:93]
	v_mfma_f32_16x16x32_bf16 v[78:81], v[154:157], v[214:217], v[78:81]
	v_mfma_f32_16x16x32_bf16 v[74:77], v[162:165], v[214:217], v[74:77]
	v_mfma_f32_16x16x32_bf16 v[126:129], v[158:161], v[190:193], v[126:129]
	v_mfma_f32_16x16x32_bf16 v[122:125], v[166:169], v[190:193], v[122:125]
	v_mfma_f32_16x16x32_bf16 v[110:113], v[158:161], v[202:205], v[110:113]
	v_mfma_f32_16x16x32_bf16 v[106:109], v[166:169], v[202:205], v[106:109]
	v_mfma_f32_16x16x32_bf16 v[94:97], v[158:161], v[210:213], v[94:97]
	v_mfma_f32_16x16x32_bf16 v[90:93], v[166:169], v[210:213], v[90:93]
	v_mfma_f32_16x16x32_bf16 v[78:81], v[158:161], v[218:221], v[78:81]
	v_mfma_f32_16x16x32_bf16 v[74:77], v[166:169], v[218:221], v[74:77]
	v_mfma_f32_16x16x32_bf16 v[118:121], v[170:173], v[186:189], v[118:121]
	v_mfma_f32_16x16x32_bf16 v[114:117], v[178:181], v[186:189], v[114:117]
	v_mfma_f32_16x16x32_bf16 v[102:105], v[170:173], v[198:201], v[102:105]
	v_mfma_f32_16x16x32_bf16 v[98:101], v[178:181], v[198:201], v[98:101]
	v_mfma_f32_16x16x32_bf16 v[86:89], v[170:173], v[206:209], v[86:89]
	v_mfma_f32_16x16x32_bf16 v[82:85], v[178:181], v[206:209], v[82:85]
	v_mfma_f32_16x16x32_bf16 v[70:73], v[170:173], v[214:217], v[70:73]
	v_mfma_f32_16x16x32_bf16 v[66:69], v[178:181], v[214:217], v[66:69]
	v_mfma_f32_16x16x32_bf16 v[118:121], v[174:177], v[190:193], v[118:121]
	v_mfma_f32_16x16x32_bf16 v[114:117], v[182:185], v[190:193], v[114:117]
	v_mfma_f32_16x16x32_bf16 v[102:105], v[174:177], v[202:205], v[102:105]
	v_mfma_f32_16x16x32_bf16 v[98:101], v[182:185], v[202:205], v[98:101]
	v_mfma_f32_16x16x32_bf16 v[86:89], v[174:177], v[210:213], v[86:89]
	v_mfma_f32_16x16x32_bf16 v[82:85], v[182:185], v[210:213], v[82:85]
	v_mfma_f32_16x16x32_bf16 v[70:73], v[174:177], v[218:221], v[70:73]
	v_mfma_f32_16x16x32_bf16 v[66:69], v[182:185], v[218:221], v[66:69]
	s_barrier
	s_setprio 0
	s_add_i32 s69, s57, s33
	s_mov_b32 m0, s69
	ds_read_b128 v[186:189], v152 offset:16384
	ds_read_b128 v[190:193], v152 offset:17408
	ds_read_b128 v[198:201], v152 offset:18432
	ds_read_b128 v[202:205], v152 offset:19456
	ds_read_b128 v[206:209], v152 offset:20480
	ds_read_b128 v[210:213], v152 offset:21504
	ds_read_b128 v[214:217], v152 offset:22528
	ds_read_b128 v[218:221], v152 offset:23552
	global_load_lds_dwordx4 v132, s[44:45]
	s_add_i32 m0, s69, 0x2000
	s_add_u32 s70, s44, 0x100000
	s_addc_u32 s71, s45, 0
	s_add_i32 s69, s58, s33
	global_load_lds_dwordx4 v136, s[44:45]
	s_mov_b32 m0, s69
	global_load_lds_dwordx4 v132, s[70:71]
	s_add_i32 m0, s69, 0x2000
	s_nop 0
	global_load_lds_dwordx4 v136, s[70:71]
	s_mov_b32 m0, s41
	s_nop 0
	global_load_lds_dwordx4 v130, s[46:47]
	s_mov_b32 m0, s50
	s_nop 0
	global_load_lds_dwordx4 v134, s[46:47]
	s_waitcnt vmcnt(8)
	s_waitcnt lgkmcnt(0)
	s_setprio 1
	s_barrier
	v_mfma_f32_16x16x32_bf16 v[62:65], v[154:157], v[186:189], v[62:65]
	v_mfma_f32_16x16x32_bf16 v[58:61], v[162:165], v[186:189], v[58:61]
	v_mfma_f32_16x16x32_bf16 v[46:49], v[154:157], v[198:201], v[46:49]
	v_mfma_f32_16x16x32_bf16 v[42:45], v[162:165], v[198:201], v[42:45]
	v_mfma_f32_16x16x32_bf16 v[30:33], v[154:157], v[206:209], v[30:33]
	v_mfma_f32_16x16x32_bf16 v[26:29], v[162:165], v[206:209], v[26:29]
	v_mfma_f32_16x16x32_bf16 v[14:17], v[154:157], v[214:217], v[14:17]
	v_mfma_f32_16x16x32_bf16 v[10:13], v[162:165], v[214:217], v[10:13]
	v_mfma_f32_16x16x32_bf16 v[62:65], v[158:161], v[190:193], v[62:65]
	v_mfma_f32_16x16x32_bf16 v[58:61], v[166:169], v[190:193], v[58:61]
	v_mfma_f32_16x16x32_bf16 v[46:49], v[158:161], v[202:205], v[46:49]
	v_mfma_f32_16x16x32_bf16 v[42:45], v[166:169], v[202:205], v[42:45]
	v_mfma_f32_16x16x32_bf16 v[30:33], v[158:161], v[210:213], v[30:33]
	v_mfma_f32_16x16x32_bf16 v[26:29], v[166:169], v[210:213], v[26:29]
	v_mfma_f32_16x16x32_bf16 v[14:17], v[158:161], v[218:221], v[14:17]
	v_mfma_f32_16x16x32_bf16 v[10:13], v[166:169], v[218:221], v[10:13]
	v_mfma_f32_16x16x32_bf16 v[54:57], v[170:173], v[186:189], v[54:57]
	v_mfma_f32_16x16x32_bf16 v[50:53], v[178:181], v[186:189], v[50:53]
	v_mfma_f32_16x16x32_bf16 v[38:41], v[170:173], v[198:201], v[38:41]
	v_mfma_f32_16x16x32_bf16 v[34:37], v[178:181], v[198:201], v[34:37]
	v_mfma_f32_16x16x32_bf16 v[22:25], v[170:173], v[206:209], v[22:25]
	v_mfma_f32_16x16x32_bf16 v[18:21], v[178:181], v[206:209], v[18:21]
	v_mfma_f32_16x16x32_bf16 v[6:9], v[170:173], v[214:217], v[6:9]
	v_mfma_f32_16x16x32_bf16 v[2:5], v[178:181], v[214:217], v[2:5]
	v_mfma_f32_16x16x32_bf16 v[54:57], v[174:177], v[190:193], v[54:57]
	v_mfma_f32_16x16x32_bf16 v[50:53], v[182:185], v[190:193], v[50:53]
	v_mfma_f32_16x16x32_bf16 v[38:41], v[174:177], v[202:205], v[38:41]
	v_mfma_f32_16x16x32_bf16 v[34:37], v[182:185], v[202:205], v[34:37]
	v_mfma_f32_16x16x32_bf16 v[22:25], v[174:177], v[210:213], v[22:25]
	v_mfma_f32_16x16x32_bf16 v[18:21], v[182:185], v[210:213], v[18:21]
	v_mfma_f32_16x16x32_bf16 v[6:9], v[174:177], v[218:221], v[6:9]
	v_mfma_f32_16x16x32_bf16 v[2:5], v[182:185], v[218:221], v[2:5]
	s_barrier
	s_setprio 0
	s_add_i32 s69, 0, 0x18000
	v_add_u32_e32 v153, s69, v148
	s_add_i32 s70, 0, 0x1c000
	ds_read_b128 v[154:157], v153
	ds_read_b128 v[158:161], v153 offset:1024
	ds_read_b128 v[162:165], v153 offset:2048
	ds_read_b128 v[166:169], v153 offset:3072
	v_add_u32_e32 v153, s70, v148
	ds_read_b128 v[170:173], v153
	ds_read_b128 v[174:177], v153 offset:1024
	ds_read_b128 v[178:181], v153 offset:2048
	ds_read_b128 v[182:185], v153 offset:3072
	s_add_u32 s46, s46, 0x100000
	s_addc_u32 s47, s47, 0
	s_mov_b32 m0, s51
	ds_read_b128 v[186:189], v152 offset:32768
	ds_read_b128 v[190:193], v152 offset:33792
	ds_read_b128 v[198:201], v152 offset:34816
	ds_read_b128 v[202:205], v152 offset:35840
	ds_read_b128 v[206:209], v152 offset:36864
	ds_read_b128 v[210:213], v152 offset:37888
	ds_read_b128 v[214:217], v152 offset:38912
	ds_read_b128 v[218:221], v152 offset:39936
	global_load_lds_dwordx4 v130, s[46:47]
	s_mov_b32 m0, s52
	s_nop 0
	global_load_lds_dwordx4 v134, s[46:47]
	s_waitcnt vmcnt(8)
	s_waitcnt lgkmcnt(0)
	s_setprio 1
	s_barrier
	v_mfma_f32_16x16x32_bf16 v[126:129], v[154:157], v[186:189], v[126:129]
	v_mfma_f32_16x16x32_bf16 v[122:125], v[162:165], v[186:189], v[122:125]
	v_mfma_f32_16x16x32_bf16 v[110:113], v[154:157], v[198:201], v[110:113]
	v_mfma_f32_16x16x32_bf16 v[106:109], v[162:165], v[198:201], v[106:109]
	v_mfma_f32_16x16x32_bf16 v[94:97], v[154:157], v[206:209], v[94:97]
	v_mfma_f32_16x16x32_bf16 v[90:93], v[162:165], v[206:209], v[90:93]
	v_mfma_f32_16x16x32_bf16 v[78:81], v[154:157], v[214:217], v[78:81]
	v_mfma_f32_16x16x32_bf16 v[74:77], v[162:165], v[214:217], v[74:77]
	v_mfma_f32_16x16x32_bf16 v[126:129], v[158:161], v[190:193], v[126:129]
	v_mfma_f32_16x16x32_bf16 v[122:125], v[166:169], v[190:193], v[122:125]
	v_mfma_f32_16x16x32_bf16 v[110:113], v[158:161], v[202:205], v[110:113]
	v_mfma_f32_16x16x32_bf16 v[106:109], v[166:169], v[202:205], v[106:109]
	v_mfma_f32_16x16x32_bf16 v[94:97], v[158:161], v[210:213], v[94:97]
	v_mfma_f32_16x16x32_bf16 v[90:93], v[166:169], v[210:213], v[90:93]
	v_mfma_f32_16x16x32_bf16 v[78:81], v[158:161], v[218:221], v[78:81]
	v_mfma_f32_16x16x32_bf16 v[74:77], v[166:169], v[218:221], v[74:77]
	v_mfma_f32_16x16x32_bf16 v[118:121], v[170:173], v[186:189], v[118:121]
	v_mfma_f32_16x16x32_bf16 v[114:117], v[178:181], v[186:189], v[114:117]
	v_mfma_f32_16x16x32_bf16 v[102:105], v[170:173], v[198:201], v[102:105]
	v_mfma_f32_16x16x32_bf16 v[98:101], v[178:181], v[198:201], v[98:101]
	v_mfma_f32_16x16x32_bf16 v[86:89], v[170:173], v[206:209], v[86:89]
	v_mfma_f32_16x16x32_bf16 v[82:85], v[178:181], v[206:209], v[82:85]
	v_mfma_f32_16x16x32_bf16 v[70:73], v[170:173], v[214:217], v[70:73]
	v_mfma_f32_16x16x32_bf16 v[66:69], v[178:181], v[214:217], v[66:69]
	v_mfma_f32_16x16x32_bf16 v[118:121], v[174:177], v[190:193], v[118:121]
	v_mfma_f32_16x16x32_bf16 v[114:117], v[182:185], v[190:193], v[114:117]
	v_mfma_f32_16x16x32_bf16 v[102:105], v[174:177], v[202:205], v[102:105]
	v_mfma_f32_16x16x32_bf16 v[98:101], v[182:185], v[202:205], v[98:101]
	v_mfma_f32_16x16x32_bf16 v[86:89], v[174:177], v[210:213], v[86:89]
	v_mfma_f32_16x16x32_bf16 v[82:85], v[182:185], v[210:213], v[82:85]
	v_mfma_f32_16x16x32_bf16 v[70:73], v[174:177], v[218:221], v[70:73]
	v_mfma_f32_16x16x32_bf16 v[66:69], v[182:185], v[218:221], v[66:69]
	s_barrier
	s_setprio 0
	s_add_u32 s44, s44, 0x80
	s_addc_u32 s45, s45, 0
	s_add_i32 m0, s33, 0x18000
	ds_read_b128 v[186:189], v152 offset:49152
	ds_read_b128 v[190:193], v152 offset:50176
	ds_read_b128 v[198:201], v152 offset:51200
	ds_read_b128 v[202:205], v152 offset:52224
	ds_read_b128 v[206:209], v152 offset:53248
	ds_read_b128 v[210:213], v152 offset:54272
	ds_read_b128 v[214:217], v152 offset:55296
	ds_read_b128 v[218:221], v152 offset:56320
	global_load_lds_dwordx4 v132, s[44:45]
	s_add_i32 m0, s33, 0x1a000
	s_add_u32 s46, s46, 0xfff00080
	global_load_lds_dwordx4 v136, s[44:45]
	s_addc_u32 s47, s47, -1
	s_add_u32 s44, s44, 0x100000
	s_addc_u32 s45, s45, 0
	s_add_i32 m0, s33, 0x1c000
	s_nop 0
	global_load_lds_dwordx4 v132, s[44:45]
	s_add_i32 m0, s33, 0x1e000
	s_nop 0
	global_load_lds_dwordx4 v136, s[44:45]
	s_mov_b32 m0, s55
	s_nop 0
	global_load_lds_dwordx4 v130, s[46:47]
	s_mov_b32 m0, s56
	s_nop 0
	global_load_lds_dwordx4 v134, s[46:47]
	s_waitcnt vmcnt(8)
	s_waitcnt lgkmcnt(0)
	s_setprio 1
	s_barrier
	v_mfma_f32_16x16x32_bf16 v[62:65], v[154:157], v[186:189], v[62:65]
	v_mfma_f32_16x16x32_bf16 v[58:61], v[162:165], v[186:189], v[58:61]
	v_mfma_f32_16x16x32_bf16 v[46:49], v[154:157], v[198:201], v[46:49]
	v_mfma_f32_16x16x32_bf16 v[42:45], v[162:165], v[198:201], v[42:45]
	v_mfma_f32_16x16x32_bf16 v[30:33], v[154:157], v[206:209], v[30:33]
	v_mfma_f32_16x16x32_bf16 v[26:29], v[162:165], v[206:209], v[26:29]
	v_mfma_f32_16x16x32_bf16 v[14:17], v[154:157], v[214:217], v[14:17]
	v_mfma_f32_16x16x32_bf16 v[10:13], v[162:165], v[214:217], v[10:13]
	v_mfma_f32_16x16x32_bf16 v[62:65], v[158:161], v[190:193], v[62:65]
	v_mfma_f32_16x16x32_bf16 v[58:61], v[166:169], v[190:193], v[58:61]
	v_mfma_f32_16x16x32_bf16 v[46:49], v[158:161], v[202:205], v[46:49]
	v_mfma_f32_16x16x32_bf16 v[42:45], v[166:169], v[202:205], v[42:45]
	v_mfma_f32_16x16x32_bf16 v[30:33], v[158:161], v[210:213], v[30:33]
	v_mfma_f32_16x16x32_bf16 v[26:29], v[166:169], v[210:213], v[26:29]
	v_mfma_f32_16x16x32_bf16 v[14:17], v[158:161], v[218:221], v[14:17]
	v_mfma_f32_16x16x32_bf16 v[10:13], v[166:169], v[218:221], v[10:13]
	v_mfma_f32_16x16x32_bf16 v[54:57], v[170:173], v[186:189], v[54:57]
	v_mfma_f32_16x16x32_bf16 v[50:53], v[178:181], v[186:189], v[50:53]
	v_mfma_f32_16x16x32_bf16 v[38:41], v[170:173], v[198:201], v[38:41]
	v_mfma_f32_16x16x32_bf16 v[34:37], v[178:181], v[198:201], v[34:37]
	v_mfma_f32_16x16x32_bf16 v[22:25], v[170:173], v[206:209], v[22:25]
	v_mfma_f32_16x16x32_bf16 v[18:21], v[178:181], v[206:209], v[18:21]
	v_mfma_f32_16x16x32_bf16 v[6:9], v[170:173], v[214:217], v[6:9]
	v_mfma_f32_16x16x32_bf16 v[2:5], v[178:181], v[214:217], v[2:5]
	v_mfma_f32_16x16x32_bf16 v[54:57], v[174:177], v[190:193], v[54:57]
	v_mfma_f32_16x16x32_bf16 v[50:53], v[182:185], v[190:193], v[50:53]
	v_mfma_f32_16x16x32_bf16 v[38:41], v[174:177], v[202:205], v[38:41]
	v_mfma_f32_16x16x32_bf16 v[34:37], v[182:185], v[202:205], v[34:37]
	v_mfma_f32_16x16x32_bf16 v[22:25], v[174:177], v[210:213], v[22:25]
	v_mfma_f32_16x16x32_bf16 v[18:21], v[182:185], v[210:213], v[18:21]
	v_mfma_f32_16x16x32_bf16 v[6:9], v[174:177], v[218:221], v[6:9]
	v_mfma_f32_16x16x32_bf16 v[2:5], v[182:185], v[218:221], v[2:5]
	s_barrier
	s_setprio 0
	s_add_i32 s68, s68, 2
	s_add_u32 s42, s42, 0x100
	s_addc_u32 s43, s43, 0
	s_add_u32 s66, s66, 0x100
	s_addc_u32 s67, s67, 0
	s_cmp_gt_u32 s68, 61
	s_cbranch_scc0 .LBB0_807
	s_and_b64 vcc, exec, s[14:15]
	s_cbranch_vccz .LBB0_810
	s_barrier

.LBB0_873:
	ds_read_b128 v[158:161], v153
	ds_read_b128 v[162:165], v153 offset:1024
	ds_read_b128 v[166:169], v153 offset:2048
	ds_read_b128 v[170:173], v153 offset:3072
	ds_read_b128 v[174:177], v154
	ds_read_b128 v[178:181], v154 offset:1024
	ds_read_b128 v[182:185], v154 offset:2048
	ds_read_b128 v[186:189], v154 offset:3072
	s_add_u32 s20, s16, s18
	s_addc_u32 s21, s17, s19
	s_add_u32 s20, s20, 0x3f400100
	s_addc_u32 s21, s21, 0
	s_add_u32 s53, s40, s18
	s_addc_u32 s54, s41, s19
	s_cmpk_eq_i32 s18, 0x3f00
	s_cselect_b32 s29, s7, s21
	s_cselect_b32 s28, s6, s20
	s_cselect_b32 s21, s5, s54
	s_cselect_b32 s20, s4, s53
	s_mov_b32 m0, s43
	v_lshl_add_u64 v[194:195], v[138:139], 0, s[18:19]
	ds_read_b128 v[190:193], v155
	ds_read_b128 v[198:201], v155 offset:1024
	ds_read_b128 v[202:205], v155 offset:2048
	ds_read_b128 v[206:209], v155 offset:3072
	ds_read_b128 v[210:213], v155 offset:4096
	ds_read_b128 v[214:217], v155 offset:5120
	ds_read_b128 v[218:221], v155 offset:6144
	ds_read_b128 v[222:225], v155 offset:7168
	global_load_lds_dwordx4 v[194:195], off
	v_lshl_add_u64 v[194:195], v[140:141], 0, s[18:19]
	s_mov_b32 m0, s44
	s_nop 0
	global_load_lds_dwordx4 v[194:195], off
	s_waitcnt vmcnt(8)
	s_waitcnt lgkmcnt(0)
	s_setprio 1
	s_barrier
	v_mfma_f32_16x16x32_bf16 v[126:129], v[158:161], v[190:193], v[126:129]
	v_mfma_f32_16x16x32_bf16 v[122:125], v[166:169], v[190:193], v[122:125]
	v_mfma_f32_16x16x32_bf16 v[110:113], v[158:161], v[202:205], v[110:113]
	v_mfma_f32_16x16x32_bf16 v[106:109], v[166:169], v[202:205], v[106:109]
	v_mfma_f32_16x16x32_bf16 v[94:97], v[158:161], v[210:213], v[94:97]
	v_mfma_f32_16x16x32_bf16 v[90:93], v[166:169], v[210:213], v[90:93]
	v_mfma_f32_16x16x32_bf16 v[78:81], v[158:161], v[218:221], v[78:81]
	v_mfma_f32_16x16x32_bf16 v[74:77], v[166:169], v[218:221], v[74:77]
	v_mfma_f32_16x16x32_bf16 v[126:129], v[162:165], v[198:201], v[126:129]
	v_mfma_f32_16x16x32_bf16 v[122:125], v[170:173], v[198:201], v[122:125]
	v_mfma_f32_16x16x32_bf16 v[110:113], v[162:165], v[206:209], v[110:113]
	v_mfma_f32_16x16x32_bf16 v[106:109], v[170:173], v[206:209], v[106:109]
	v_mfma_f32_16x16x32_bf16 v[94:97], v[162:165], v[214:217], v[94:97]
	v_mfma_f32_16x16x32_bf16 v[90:93], v[170:173], v[214:217], v[90:93]
	v_mfma_f32_16x16x32_bf16 v[78:81], v[162:165], v[222:225], v[78:81]
	v_mfma_f32_16x16x32_bf16 v[74:77], v[170:173], v[222:225], v[74:77]
	v_mfma_f32_16x16x32_bf16 v[118:121], v[174:177], v[190:193], v[118:121]
	v_mfma_f32_16x16x32_bf16 v[114:117], v[182:185], v[190:193], v[114:117]
	v_mfma_f32_16x16x32_bf16 v[102:105], v[174:177], v[202:205], v[102:105]
	v_mfma_f32_16x16x32_bf16 v[98:101], v[182:185], v[202:205], v[98:101]
	v_mfma_f32_16x16x32_bf16 v[86:89], v[174:177], v[210:213], v[86:89]
	v_mfma_f32_16x16x32_bf16 v[82:85], v[182:185], v[210:213], v[82:85]
	v_mfma_f32_16x16x32_bf16 v[70:73], v[174:177], v[218:221], v[70:73]
	v_mfma_f32_16x16x32_bf16 v[66:69], v[182:185], v[218:221], v[66:69]
	v_mfma_f32_16x16x32_bf16 v[118:121], v[178:181], v[198:201], v[118:121]
	v_mfma_f32_16x16x32_bf16 v[114:117], v[186:189], v[198:201], v[114:117]
	v_mfma_f32_16x16x32_bf16 v[102:105], v[178:181], v[206:209], v[102:105]
	v_mfma_f32_16x16x32_bf16 v[98:101], v[186:189], v[206:209], v[98:101]
	v_mfma_f32_16x16x32_bf16 v[86:89], v[178:181], v[214:217], v[86:89]
	v_mfma_f32_16x16x32_bf16 v[82:85], v[186:189], v[214:217], v[82:85]
	v_mfma_f32_16x16x32_bf16 v[70:73], v[178:181], v[222:225], v[70:73]
	v_mfma_f32_16x16x32_bf16 v[66:69], v[186:189], v[222:225], v[66:69]
	s_barrier
	s_setprio 0
	s_mov_b32 m0, s45
	v_lshl_add_u64 v[194:195], s[20:21], 0, v[134:135]
	s_add_u32 s54, s20, 0x400000
	ds_read_b128 v[190:193], v155 offset:16384
	ds_read_b128 v[198:201], v155 offset:17408
	ds_read_b128 v[202:205], v155 offset:18432
	ds_read_b128 v[206:209], v155 offset:19456
	ds_read_b128 v[210:213], v155 offset:20480
	ds_read_b128 v[214:217], v155 offset:21504
	ds_read_b128 v[218:221], v155 offset:22528
	ds_read_b128 v[222:225], v155 offset:23552
	global_load_lds_dwordx4 v[194:195], off
	v_lshl_add_u64 v[226:227], s[20:21], 0, v[130:131]
	s_mov_b32 m0, s46
	s_addc_u32 s55, s21, 0
	global_load_lds_dwordx4 v[226:227], off
	v_lshl_add_u64 v[228:229], s[54:55], 0, v[134:135]
	s_mov_b32 m0, s47
	v_lshl_add_u64 v[230:231], s[28:29], 0, v[132:133]
	global_load_lds_dwordx4 v[228:229], off
	v_lshl_add_u64 v[228:229], s[54:55], 0, v[130:131]
	s_mov_b32 m0, s48
	s_nop 0
	global_load_lds_dwordx4 v[228:229], off
	v_lshl_add_u64 v[228:229], s[28:29], 0, v[136:137]
	s_mov_b32 m0, s0
	s_nop 0
	global_load_lds_dwordx4 v[228:229], off
	s_mov_b32 m0, s34
	s_nop 0
	global_load_lds_dwordx4 v[230:231], off
	s_waitcnt vmcnt(8)
	s_waitcnt lgkmcnt(0)
	s_setprio 1
	s_barrier
	v_mfma_f32_16x16x32_bf16 v[62:65], v[158:161], v[190:193], v[62:65]
	v_mfma_f32_16x16x32_bf16 v[58:61], v[166:169], v[190:193], v[58:61]
	v_mfma_f32_16x16x32_bf16 v[46:49], v[158:161], v[202:205], v[46:49]
	v_mfma_f32_16x16x32_bf16 v[42:45], v[166:169], v[202:205], v[42:45]
	v_mfma_f32_16x16x32_bf16 v[30:33], v[158:161], v[210:213], v[30:33]
	v_mfma_f32_16x16x32_bf16 v[26:29], v[166:169], v[210:213], v[26:29]
	v_mfma_f32_16x16x32_bf16 v[14:17], v[158:161], v[218:221], v[14:17]
	v_mfma_f32_16x16x32_bf16 v[10:13], v[166:169], v[218:221], v[10:13]
	v_mfma_f32_16x16x32_bf16 v[62:65], v[162:165], v[198:201], v[62:65]
	v_mfma_f32_16x16x32_bf16 v[58:61], v[170:173], v[198:201], v[58:61]
	v_mfma_f32_16x16x32_bf16 v[46:49], v[162:165], v[206:209], v[46:49]
	v_mfma_f32_16x16x32_bf16 v[42:45], v[170:173], v[206:209], v[42:45]
	v_mfma_f32_16x16x32_bf16 v[30:33], v[162:165], v[214:217], v[30:33]
	v_mfma_f32_16x16x32_bf16 v[26:29], v[170:173], v[214:217], v[26:29]
	v_mfma_f32_16x16x32_bf16 v[14:17], v[162:165], v[222:225], v[14:17]
	v_mfma_f32_16x16x32_bf16 v[10:13], v[170:173], v[222:225], v[10:13]
	v_mfma_f32_16x16x32_bf16 v[54:57], v[174:177], v[190:193], v[54:57]
	v_mfma_f32_16x16x32_bf16 v[50:53], v[182:185], v[190:193], v[50:53]
	v_mfma_f32_16x16x32_bf16 v[38:41], v[174:177], v[202:205], v[38:41]
	v_mfma_f32_16x16x32_bf16 v[34:37], v[182:185], v[202:205], v[34:37]
	v_mfma_f32_16x16x32_bf16 v[22:25], v[174:177], v[210:213], v[22:25]
	v_mfma_f32_16x16x32_bf16 v[18:21], v[182:185], v[210:213], v[18:21]
	v_mfma_f32_16x16x32_bf16 v[6:9], v[174:177], v[218:221], v[6:9]
	v_mfma_f32_16x16x32_bf16 v[2:5], v[182:185], v[218:221], v[2:5]
	v_mfma_f32_16x16x32_bf16 v[54:57], v[178:181], v[198:201], v[54:57]
	v_mfma_f32_16x16x32_bf16 v[50:53], v[186:189], v[198:201], v[50:53]
	v_mfma_f32_16x16x32_bf16 v[38:41], v[178:181], v[206:209], v[38:41]
	v_mfma_f32_16x16x32_bf16 v[34:37], v[186:189], v[206:209], v[34:37]
	v_mfma_f32_16x16x32_bf16 v[22:25], v[178:181], v[214:217], v[22:25]
	v_mfma_f32_16x16x32_bf16 v[18:21], v[186:189], v[214:217], v[18:21]
	v_mfma_f32_16x16x32_bf16 v[6:9], v[178:181], v[222:225], v[6:9]
	v_mfma_f32_16x16x32_bf16 v[2:5], v[186:189], v[222:225], v[2:5]
	s_barrier
	s_setprio 0
	ds_read_b128 v[158:161], v156
	ds_read_b128 v[162:165], v156 offset:1024
	ds_read_b128 v[166:169], v156 offset:2048
	ds_read_b128 v[170:173], v156 offset:3072
	ds_read_b128 v[174:177], v157
	ds_read_b128 v[178:181], v157 offset:1024
	ds_read_b128 v[182:185], v157 offset:2048
	ds_read_b128 v[186:189], v157 offset:3072
	s_add_u32 s28, s28, 0x400000
	s_addc_u32 s29, s29, 0
	s_mov_b32 m0, s36
	v_lshl_add_u64 v[232:233], s[28:29], 0, v[136:137]
	ds_read_b128 v[190:193], v155 offset:32768
	ds_read_b128 v[198:201], v155 offset:33792
	ds_read_b128 v[202:205], v155 offset:34816
	ds_read_b128 v[206:209], v155 offset:35840
	ds_read_b128 v[210:213], v155 offset:36864
	ds_read_b128 v[214:217], v155 offset:37888
	ds_read_b128 v[218:221], v155 offset:38912
	ds_read_b128 v[222:225], v155 offset:39936
	global_load_lds_dwordx4 v[232:233], off
	v_lshl_add_u64 v[232:233], s[28:29], 0, v[132:133]
	s_mov_b32 m0, s37
	s_nop 0
	global_load_lds_dwordx4 v[232:233], off
	s_waitcnt vmcnt(8)
	s_waitcnt lgkmcnt(0)
	s_setprio 1
	s_barrier
	v_mfma_f32_16x16x32_bf16 v[126:129], v[158:161], v[190:193], v[126:129]
	v_mfma_f32_16x16x32_bf16 v[122:125], v[166:169], v[190:193], v[122:125]
	v_mfma_f32_16x16x32_bf16 v[110:113], v[158:161], v[202:205], v[110:113]
	v_mfma_f32_16x16x32_bf16 v[106:109], v[166:169], v[202:205], v[106:109]
	v_mfma_f32_16x16x32_bf16 v[94:97], v[158:161], v[210:213], v[94:97]
	v_mfma_f32_16x16x32_bf16 v[90:93], v[166:169], v[210:213], v[90:93]
	v_mfma_f32_16x16x32_bf16 v[78:81], v[158:161], v[218:221], v[78:81]
	v_mfma_f32_16x16x32_bf16 v[74:77], v[166:169], v[218:221], v[74:77]
	v_mfma_f32_16x16x32_bf16 v[126:129], v[162:165], v[198:201], v[126:129]
	v_mfma_f32_16x16x32_bf16 v[122:125], v[170:173], v[198:201], v[122:125]
	v_mfma_f32_16x16x32_bf16 v[110:113], v[162:165], v[206:209], v[110:113]
	v_mfma_f32_16x16x32_bf16 v[106:109], v[170:173], v[206:209], v[106:109]
	v_mfma_f32_16x16x32_bf16 v[94:97], v[162:165], v[214:217], v[94:97]
	v_mfma_f32_16x16x32_bf16 v[90:93], v[170:173], v[214:217], v[90:93]
	v_mfma_f32_16x16x32_bf16 v[78:81], v[162:165], v[222:225], v[78:81]
	v_mfma_f32_16x16x32_bf16 v[74:77], v[170:173], v[222:225], v[74:77]
	v_mfma_f32_16x16x32_bf16 v[118:121], v[174:177], v[190:193], v[118:121]
	v_mfma_f32_16x16x32_bf16 v[114:117], v[182:185], v[190:193], v[114:117]
	v_mfma_f32_16x16x32_bf16 v[102:105], v[174:177], v[202:205], v[102:105]
	v_mfma_f32_16x16x32_bf16 v[98:101], v[182:185], v[202:205], v[98:101]
	v_mfma_f32_16x16x32_bf16 v[86:89], v[174:177], v[210:213], v[86:89]
	v_mfma_f32_16x16x32_bf16 v[82:85], v[182:185], v[210:213], v[82:85]
	v_mfma_f32_16x16x32_bf16 v[70:73], v[174:177], v[218:221], v[70:73]
	v_mfma_f32_16x16x32_bf16 v[66:69], v[182:185], v[218:221], v[66:69]
	v_mfma_f32_16x16x32_bf16 v[118:121], v[178:181], v[198:201], v[118:121]
	v_mfma_f32_16x16x32_bf16 v[114:117], v[186:189], v[198:201], v[114:117]
	v_mfma_f32_16x16x32_bf16 v[102:105], v[178:181], v[206:209], v[102:105]
	v_mfma_f32_16x16x32_bf16 v[98:101], v[186:189], v[206:209], v[98:101]
	v_mfma_f32_16x16x32_bf16 v[86:89], v[178:181], v[214:217], v[86:89]
	v_mfma_f32_16x16x32_bf16 v[82:85], v[186:189], v[214:217], v[82:85]
	v_mfma_f32_16x16x32_bf16 v[70:73], v[178:181], v[222:225], v[70:73]
	v_mfma_f32_16x16x32_bf16 v[66:69], v[186:189], v[222:225], v[66:69]
	s_barrier
	s_setprio 0
	s_mov_b32 m0, s49
	v_lshl_add_u64 v[194:195], v[194:195], 0, s[14:15]
	s_add_u32 s20, s20, 0x400080
	ds_read_b128 v[190:193], v155 offset:49152
	ds_read_b128 v[198:201], v155 offset:50176
	ds_read_b128 v[202:205], v155 offset:51200
	ds_read_b128 v[206:209], v155 offset:52224
	ds_read_b128 v[210:213], v155 offset:53248
	ds_read_b128 v[214:217], v155 offset:54272
	ds_read_b128 v[218:221], v155 offset:55296
	ds_read_b128 v[222:225], v155 offset:56320
	global_load_lds_dwordx4 v[194:195], off
	v_lshl_add_u64 v[194:195], v[226:227], 0, s[14:15]
	s_mov_b32 m0, s50
	s_addc_u32 s21, s21, 0
	global_load_lds_dwordx4 v[194:195], off
	v_lshl_add_u64 v[194:195], s[20:21], 0, v[134:135]
	s_mov_b32 m0, s51
	s_nop 0
	global_load_lds_dwordx4 v[194:195], off
	v_lshl_add_u64 v[194:195], s[20:21], 0, v[130:131]
	s_mov_b32 m0, s52
	s_nop 0
	global_load_lds_dwordx4 v[194:195], off
	v_lshl_add_u64 v[194:195], v[228:229], 0, s[14:15]
	s_mov_b32 m0, s38
	s_nop 0
	global_load_lds_dwordx4 v[194:195], off
	v_lshl_add_u64 v[194:195], v[230:231], 0, s[14:15]
	s_mov_b32 m0, s39
	s_nop 0
	global_load_lds_dwordx4 v[194:195], off
	s_waitcnt vmcnt(8)
	s_waitcnt lgkmcnt(0)
	s_setprio 1
	s_barrier
	v_mfma_f32_16x16x32_bf16 v[62:65], v[158:161], v[190:193], v[62:65]
	v_mfma_f32_16x16x32_bf16 v[58:61], v[166:169], v[190:193], v[58:61]
	v_mfma_f32_16x16x32_bf16 v[46:49], v[158:161], v[202:205], v[46:49]
	v_mfma_f32_16x16x32_bf16 v[42:45], v[166:169], v[202:205], v[42:45]
	v_mfma_f32_16x16x32_bf16 v[30:33], v[158:161], v[210:213], v[30:33]
	v_mfma_f32_16x16x32_bf16 v[26:29], v[166:169], v[210:213], v[26:29]
	v_mfma_f32_16x16x32_bf16 v[14:17], v[158:161], v[218:221], v[14:17]
	v_mfma_f32_16x16x32_bf16 v[10:13], v[166:169], v[218:221], v[10:13]
	v_mfma_f32_16x16x32_bf16 v[62:65], v[162:165], v[198:201], v[62:65]
	v_mfma_f32_16x16x32_bf16 v[58:61], v[170:173], v[198:201], v[58:61]
	v_mfma_f32_16x16x32_bf16 v[46:49], v[162:165], v[206:209], v[46:49]
	v_mfma_f32_16x16x32_bf16 v[42:45], v[170:173], v[206:209], v[42:45]
	v_mfma_f32_16x16x32_bf16 v[30:33], v[162:165], v[214:217], v[30:33]
	v_mfma_f32_16x16x32_bf16 v[26:29], v[170:173], v[214:217], v[26:29]
	v_mfma_f32_16x16x32_bf16 v[14:17], v[162:165], v[222:225], v[14:17]
	v_mfma_f32_16x16x32_bf16 v[10:13], v[170:173], v[222:225], v[10:13]
	v_mfma_f32_16x16x32_bf16 v[54:57], v[174:177], v[190:193], v[54:57]
	v_mfma_f32_16x16x32_bf16 v[50:53], v[182:185], v[190:193], v[50:53]
	v_mfma_f32_16x16x32_bf16 v[38:41], v[174:177], v[202:205], v[38:41]
	v_mfma_f32_16x16x32_bf16 v[34:37], v[182:185], v[202:205], v[34:37]
	v_mfma_f32_16x16x32_bf16 v[22:25], v[174:177], v[210:213], v[22:25]
	v_mfma_f32_16x16x32_bf16 v[18:21], v[182:185], v[210:213], v[18:21]
	v_mfma_f32_16x16x32_bf16 v[6:9], v[174:177], v[218:221], v[6:9]
	v_mfma_f32_16x16x32_bf16 v[2:5], v[182:185], v[218:221], v[2:5]
	v_mfma_f32_16x16x32_bf16 v[54:57], v[178:181], v[198:201], v[54:57]
	v_mfma_f32_16x16x32_bf16 v[50:53], v[186:189], v[198:201], v[50:53]
	v_mfma_f32_16x16x32_bf16 v[38:41], v[178:181], v[206:209], v[38:41]
	v_mfma_f32_16x16x32_bf16 v[34:37], v[186:189], v[206:209], v[34:37]
	v_mfma_f32_16x16x32_bf16 v[22:25], v[178:181], v[214:217], v[22:25]
	v_mfma_f32_16x16x32_bf16 v[18:21], v[186:189], v[214:217], v[18:21]
	v_mfma_f32_16x16x32_bf16 v[6:9], v[178:181], v[222:225], v[6:9]
	v_mfma_f32_16x16x32_bf16 v[2:5], v[186:189], v[222:225], v[2:5]
	s_barrier
	s_setprio 0
	s_add_i32 s42, s42, 2
	s_add_u32 s18, s18, 0x100
	s_addc_u32 s19, s19, 0
	s_cmpk_gt_u32 s42, 0x7d
	s_cbranch_scc0 .LBB0_873
	s_lshl_b32 s0, s33, 25
	s_add_u32 s0, s22, s0
	s_addc_u32 s5, s23, 0
	s_add_u32 s4, s0, 0x43800000
	s_addc_u32 s5, s5, 0
	s_add_u32 s6, s22, 0x20000
	s_addc_u32 s7, s23, 0
	v_lshl_add_u32 v130, s31, 8, v152
	v_mov_b32_e32 v131, 0
	v_lshl_add_u64 v[132:133], v[130:131], 2, s[6:7]
	global_load_dword v137, v[132:133], off
	v_mov_b32_e32 v136, 0x358637bd
	v_lshl_or_b32 v134, s1, 8, v142
	v_or_b32_e32 v134, s35, v134
	v_lshlrev_b64 v[138:139], 14, v[130:131]
	v_ashrrev_i32_e32 v135, 31, v134
	v_lshlrev_b64 v[134:135], 2, v[134:135]
	v_lshl_add_u64 v[138:139], s[4:5], 0, v[138:139]
	v_or_b32_e32 v140, 16, v130
	v_mov_b32_e32 v141, v131
	v_lshl_add_u64 v[138:139], v[138:139], 0, v[134:135]
	v_lshl_add_u64 v[152:153], v[140:141], 2, s[6:7]
	s_cmpk_lt_u32 s30, 0x100
	s_waitcnt vmcnt(0)
	v_fmamk_f32 v137, v137, 0x39800000, v136
	v_div_scale_f32 v154, s[0:1], v137, v137, 1.0
	v_rcp_f32_e32 v155, v154
	v_div_scale_f32 v156, vcc, 1.0, v137, 1.0
	v_fma_f32 v157, -v154, v155, 1.0
	v_fmac_f32_e32 v155, v157, v155
	v_mul_f32_e32 v157, v156, v155
	v_fma_f32 v158, -v154, v157, v156
	v_fmac_f32_e32 v157, v158, v155
	v_fma_f32 v154, -v154, v157, v156
	v_div_fmas_f32 v154, v154, v155, v157
	v_div_fixup_f32 v154, v154, v137, 1.0
	v_pk_mul_f32 v[128:129], v[128:129], v[154:155] op_sel_hi:[1,0]
	v_pk_mul_f32 v[126:127], v[126:127], v[154:155] op_sel_hi:[1,0]
	v_pk_mul_f32 v[124:125], v[124:125], v[154:155] op_sel_hi:[1,0]
	v_pk_mul_f32 v[122:123], v[122:123], v[154:155] op_sel_hi:[1,0]
	v_pk_mul_f32 v[120:121], v[120:121], v[154:155] op_sel_hi:[1,0]
	v_pk_mul_f32 v[118:119], v[118:119], v[154:155] op_sel_hi:[1,0]
	v_pk_mul_f32 v[116:117], v[116:117], v[154:155] op_sel_hi:[1,0]
	v_pk_mul_f32 v[114:115], v[114:115], v[154:155] op_sel_hi:[1,0]
	global_store_dwordx4 v[138:139], v[126:129], off
	global_store_dwordx4 v[138:139], v[122:125], off offset:16
	global_store_dwordx4 v[138:139], v[118:121], off offset:512
	global_store_dwordx4 v[138:139], v[114:117], off offset:528
	global_load_dword v118, v[152:153], off
	s_waitcnt vmcnt(0)
	v_fmamk_f32 v120, v118, 0x39800000, v136
	v_div_scale_f32 v121, s[0:1], v120, v120, 1.0
	v_rcp_f32_e32 v122, v121
	v_div_scale_f32 v123, vcc, 1.0, v120, 1.0
	v_lshlrev_b64 v[116:117], 14, v[140:141]
	v_fma_f32 v124, -v121, v122, 1.0
	v_fmac_f32_e32 v122, v124, v122
	v_mul_f32_e32 v124, v123, v122
	v_fma_f32 v125, -v121, v124, v123
	v_fmac_f32_e32 v124, v125, v122
	v_fma_f32 v121, -v121, v124, v123
	v_div_fmas_f32 v121, v121, v122, v124
	v_lshl_add_u64 v[116:117], s[4:5], 0, v[116:117]
	v_div_fixup_f32 v120, v121, v120, 1.0
	v_or_b32_e32 v114, 32, v130
	v_mov_b32_e32 v115, v131
	v_lshl_add_u64 v[116:117], v[116:117], 0, v[134:135]
	v_pk_mul_f32 v[112:113], v[112:113], v[120:121] op_sel_hi:[1,0]
	v_pk_mul_f32 v[110:111], v[110:111], v[120:121] op_sel_hi:[1,0]
	v_lshl_add_u64 v[118:119], v[114:115], 2, s[6:7]
	v_pk_mul_f32 v[108:109], v[108:109], v[120:121] op_sel_hi:[1,0]
	v_pk_mul_f32 v[106:107], v[106:107], v[120:121] op_sel_hi:[1,0]
	v_pk_mul_f32 v[104:105], v[104:105], v[120:121] op_sel_hi:[1,0]
	v_pk_mul_f32 v[102:103], v[102:103], v[120:121] op_sel_hi:[1,0]
	v_pk_mul_f32 v[100:101], v[100:101], v[120:121] op_sel_hi:[1,0]
	v_pk_mul_f32 v[98:99], v[98:99], v[120:121] op_sel_hi:[1,0]
	global_store_dwordx4 v[116:117], v[110:113], off
	global_store_dwordx4 v[116:117], v[106:109], off offset:16
	global_store_dwordx4 v[116:117], v[102:105], off offset:512
	global_store_dwordx4 v[116:117], v[98:101], off offset:528
	global_load_dword v102, v[118:119], off
	s_waitcnt vmcnt(0)
	v_fmamk_f32 v104, v102, 0x39800000, v136
	v_div_scale_f32 v105, s[0:1], v104, v104, 1.0
	v_rcp_f32_e32 v106, v105
	v_div_scale_f32 v107, vcc, 1.0, v104, 1.0
	v_lshlrev_b64 v[100:101], 14, v[114:115]
	v_fma_f32 v108, -v105, v106, 1.0
	v_fmac_f32_e32 v106, v108, v106
	v_mul_f32_e32 v108, v107, v106
	v_fma_f32 v109, -v105, v108, v107
	v_fmac_f32_e32 v108, v109, v106
	v_fma_f32 v105, -v105, v108, v107
	v_div_fmas_f32 v105, v105, v106, v108
	v_lshl_add_u64 v[100:101], s[4:5], 0, v[100:101]
	v_div_fixup_f32 v104, v105, v104, 1.0
	v_or_b32_e32 v98, 48, v130
	v_mov_b32_e32 v99, v131
	v_lshl_add_u64 v[100:101], v[100:101], 0, v[134:135]
	v_pk_mul_f32 v[96:97], v[96:97], v[104:105] op_sel_hi:[1,0]
	v_pk_mul_f32 v[94:95], v[94:95], v[104:105] op_sel_hi:[1,0]
	v_lshl_add_u64 v[102:103], v[98:99], 2, s[6:7]
	v_pk_mul_f32 v[92:93], v[92:93], v[104:105] op_sel_hi:[1,0]
	v_pk_mul_f32 v[90:91], v[90:91], v[104:105] op_sel_hi:[1,0]
	v_pk_mul_f32 v[88:89], v[88:89], v[104:105] op_sel_hi:[1,0]
	v_pk_mul_f32 v[86:87], v[86:87], v[104:105] op_sel_hi:[1,0]
	v_pk_mul_f32 v[84:85], v[84:85], v[104:105] op_sel_hi:[1,0]
	v_pk_mul_f32 v[82:83], v[82:83], v[104:105] op_sel_hi:[1,0]
	global_store_dwordx4 v[100:101], v[94:97], off
	global_store_dwordx4 v[100:101], v[90:93], off offset:16
	global_store_dwordx4 v[100:101], v[86:89], off offset:512
	global_store_dwordx4 v[100:101], v[82:85], off offset:528
	global_load_dword v84, v[102:103], off
	s_nop 0
	v_lshlrev_b64 v[82:83], 14, v[98:99]
	v_lshl_add_u64 v[82:83], s[4:5], 0, v[82:83]
	v_lshl_add_u64 v[82:83], v[82:83], 0, v[134:135]
	s_waitcnt vmcnt(0)
	v_fmamk_f32 v84, v84, 0x39800000, v136
	v_div_scale_f32 v85, s[0:1], v84, v84, 1.0
	v_rcp_f32_e32 v86, v85
	v_div_scale_f32 v87, vcc, 1.0, v84, 1.0
	v_fma_f32 v88, -v85, v86, 1.0
	v_fmac_f32_e32 v86, v88, v86
	v_mul_f32_e32 v88, v87, v86
	v_fma_f32 v89, -v85, v88, v87
	v_fmac_f32_e32 v88, v89, v86
	v_fma_f32 v85, -v85, v88, v87
	v_div_fmas_f32 v85, v85, v86, v88
	v_div_fixup_f32 v84, v85, v84, 1.0
	v_pk_mul_f32 v[80:81], v[80:81], v[84:85] op_sel_hi:[1,0]
	v_pk_mul_f32 v[78:79], v[78:79], v[84:85] op_sel_hi:[1,0]
	v_pk_mul_f32 v[76:77], v[76:77], v[84:85] op_sel_hi:[1,0]
	v_pk_mul_f32 v[74:75], v[74:75], v[84:85] op_sel_hi:[1,0]
	v_pk_mul_f32 v[72:73], v[72:73], v[84:85] op_sel_hi:[1,0]
	v_pk_mul_f32 v[70:71], v[70:71], v[84:85] op_sel_hi:[1,0]
	v_pk_mul_f32 v[68:69], v[68:69], v[84:85] op_sel_hi:[1,0]
	v_pk_mul_f32 v[66:67], v[66:67], v[84:85] op_sel_hi:[1,0]
	global_store_dwordx4 v[82:83], v[78:81], off
	global_store_dwordx4 v[82:83], v[74:77], off offset:16
	global_store_dwordx4 v[82:83], v[70:73], off offset:512
	global_store_dwordx4 v[82:83], v[66:69], off offset:528
	global_load_dword v68, v[132:133], off offset:512
	s_nop 0
	v_add_u32_e32 v66, 0x80, v130
	v_mov_b32_e32 v67, v131
	v_lshlrev_b64 v[66:67], 14, v[66:67]
	v_lshl_add_u64 v[66:67], s[4:5], 0, v[66:67]
	v_lshl_add_u64 v[66:67], v[66:67], 0, v[134:135]
	s_waitcnt vmcnt(0)
	v_fmamk_f32 v68, v68, 0x39800000, v136
	v_div_scale_f32 v69, s[0:1], v68, v68, 1.0
	v_rcp_f32_e32 v70, v69
	v_div_scale_f32 v71, vcc, 1.0, v68, 1.0
	v_fma_f32 v72, -v69, v70, 1.0
	v_fmac_f32_e32 v70, v72, v70
	v_mul_f32_e32 v72, v71, v70
	v_fma_f32 v73, -v69, v72, v71
	v_fmac_f32_e32 v72, v73, v70
	v_fma_f32 v69, -v69, v72, v71
	v_div_fmas_f32 v69, v69, v70, v72
	v_div_fixup_f32 v68, v69, v68, 1.0
	v_pk_mul_f32 v[64:65], v[64:65], v[68:69] op_sel_hi:[1,0]
	v_pk_mul_f32 v[62:63], v[62:63], v[68:69] op_sel_hi:[1,0]
	v_pk_mul_f32 v[60:61], v[60:61], v[68:69] op_sel_hi:[1,0]
	v_pk_mul_f32 v[58:59], v[58:59], v[68:69] op_sel_hi:[1,0]
	v_pk_mul_f32 v[56:57], v[56:57], v[68:69] op_sel_hi:[1,0]
	v_pk_mul_f32 v[54:55], v[54:55], v[68:69] op_sel_hi:[1,0]
	v_pk_mul_f32 v[52:53], v[52:53], v[68:69] op_sel_hi:[1,0]
	v_pk_mul_f32 v[50:51], v[50:51], v[68:69] op_sel_hi:[1,0]
	global_store_dwordx4 v[66:67], v[62:65], off
	global_store_dwordx4 v[66:67], v[58:61], off offset:16
	global_store_dwordx4 v[66:67], v[54:57], off offset:512
	global_store_dwordx4 v[66:67], v[50:53], off offset:528
	global_load_dword v52, v[132:133], off offset:576
	s_nop 0
	v_add_u32_e32 v50, 0x90, v130
	v_mov_b32_e32 v51, v131
	v_lshlrev_b64 v[50:51], 14, v[50:51]
	v_lshl_add_u64 v[50:51], s[4:5], 0, v[50:51]
	v_lshl_add_u64 v[50:51], v[50:51], 0, v[134:135]
	s_waitcnt vmcnt(0)
	v_fmamk_f32 v52, v52, 0x39800000, v136
	v_div_scale_f32 v53, s[0:1], v52, v52, 1.0
	v_rcp_f32_e32 v54, v53
	v_div_scale_f32 v55, vcc, 1.0, v52, 1.0
	v_fma_f32 v56, -v53, v54, 1.0
	v_fmac_f32_e32 v54, v56, v54
	v_mul_f32_e32 v56, v55, v54
	v_fma_f32 v57, -v53, v56, v55
	v_fmac_f32_e32 v56, v57, v54
	v_fma_f32 v53, -v53, v56, v55
	v_div_fmas_f32 v53, v53, v54, v56
	v_div_fixup_f32 v52, v53, v52, 1.0
	v_pk_mul_f32 v[48:49], v[48:49], v[52:53] op_sel_hi:[1,0]
	v_pk_mul_f32 v[46:47], v[46:47], v[52:53] op_sel_hi:[1,0]
	v_pk_mul_f32 v[44:45], v[44:45], v[52:53] op_sel_hi:[1,0]
	v_pk_mul_f32 v[42:43], v[42:43], v[52:53] op_sel_hi:[1,0]
	v_pk_mul_f32 v[40:41], v[40:41], v[52:53] op_sel_hi:[1,0]
	v_pk_mul_f32 v[38:39], v[38:39], v[52:53] op_sel_hi:[1,0]
	v_pk_mul_f32 v[36:37], v[36:37], v[52:53] op_sel_hi:[1,0]
	v_pk_mul_f32 v[34:35], v[34:35], v[52:53] op_sel_hi:[1,0]
	global_store_dwordx4 v[50:51], v[46:49], off
	global_store_dwordx4 v[50:51], v[42:45], off offset:16
	global_store_dwordx4 v[50:51], v[38:41], off offset:512
	global_store_dwordx4 v[50:51], v[34:37], off offset:528
	global_load_dword v36, v[132:133], off offset:640
	s_nop 0
	v_add_u32_e32 v34, 0xa0, v130
	v_mov_b32_e32 v35, v131
	v_lshlrev_b64 v[34:35], 14, v[34:35]
	v_lshl_add_u64 v[34:35], s[4:5], 0, v[34:35]
	v_lshl_add_u64 v[34:35], v[34:35], 0, v[134:135]
	v_add_u32_e32 v130, 0xb0, v130
	s_waitcnt vmcnt(0)
	v_fmamk_f32 v36, v36, 0x39800000, v136
	v_div_scale_f32 v37, s[0:1], v36, v36, 1.0
	v_rcp_f32_e32 v38, v37
	v_div_scale_f32 v39, vcc, 1.0, v36, 1.0
	v_fma_f32 v40, -v37, v38, 1.0
	v_fmac_f32_e32 v38, v40, v38
	v_mul_f32_e32 v40, v39, v38
	v_fma_f32 v41, -v37, v40, v39
	v_fmac_f32_e32 v40, v41, v38
	v_fma_f32 v37, -v37, v40, v39
	v_div_fmas_f32 v37, v37, v38, v40
	v_div_fixup_f32 v36, v37, v36, 1.0
	v_pk_mul_f32 v[32:33], v[32:33], v[36:37] op_sel_hi:[1,0]
	v_pk_mul_f32 v[30:31], v[30:31], v[36:37] op_sel_hi:[1,0]
	v_pk_mul_f32 v[28:29], v[28:29], v[36:37] op_sel_hi:[1,0]
	v_pk_mul_f32 v[26:27], v[26:27], v[36:37] op_sel_hi:[1,0]
	v_pk_mul_f32 v[24:25], v[24:25], v[36:37] op_sel_hi:[1,0]
	v_pk_mul_f32 v[22:23], v[22:23], v[36:37] op_sel_hi:[1,0]
	v_pk_mul_f32 v[20:21], v[20:21], v[36:37] op_sel_hi:[1,0]
	v_pk_mul_f32 v[18:19], v[18:19], v[36:37] op_sel_hi:[1,0]
	global_store_dwordx4 v[34:35], v[30:33], off
	global_store_dwordx4 v[34:35], v[26:29], off offset:16
	global_store_dwordx4 v[34:35], v[22:25], off offset:512
	global_store_dwordx4 v[34:35], v[18:21], off offset:528
	global_load_dword v20, v[132:133], off offset:704
	s_waitcnt vmcnt(0)
	v_fmac_f32_e32 v136, 0x39800000, v20
	v_div_scale_f32 v20, s[0:1], v136, v136, 1.0
	v_rcp_f32_e32 v21, v20
	v_div_scale_f32 v22, vcc, 1.0, v136, 1.0
	v_lshlrev_b64 v[18:19], 14, v[130:131]
	v_fma_f32 v23, -v20, v21, 1.0
	v_fmac_f32_e32 v21, v23, v21
	v_mul_f32_e32 v23, v22, v21
	v_fma_f32 v24, -v20, v23, v22
	v_fmac_f32_e32 v23, v24, v21
	v_fma_f32 v20, -v20, v23, v22
	v_div_fmas_f32 v20, v20, v21, v23
	v_lshl_add_u64 v[18:19], s[4:5], 0, v[18:19]
	v_div_fixup_f32 v20, v20, v136, 1.0
	v_lshl_add_u64 v[18:19], v[18:19], 0, v[134:135]
	v_pk_mul_f32 v[16:17], v[16:17], v[20:21] op_sel_hi:[1,0]
	v_pk_mul_f32 v[14:15], v[14:15], v[20:21] op_sel_hi:[1,0]
	v_pk_mul_f32 v[12:13], v[12:13], v[20:21] op_sel_hi:[1,0]
	v_pk_mul_f32 v[10:11], v[10:11], v[20:21] op_sel_hi:[1,0]
	v_pk_mul_f32 v[8:9], v[8:9], v[20:21] op_sel_hi:[1,0]
	v_pk_mul_f32 v[6:7], v[6:7], v[20:21] op_sel_hi:[1,0]
	v_pk_mul_f32 v[4:5], v[4:5], v[20:21] op_sel_hi:[1,0]
	v_pk_mul_f32 v[2:3], v[2:3], v[20:21] op_sel_hi:[1,0]
	global_store_dwordx4 v[18:19], v[14:17], off
	global_store_dwordx4 v[18:19], v[10:13], off offset:16
	global_store_dwordx4 v[18:19], v[6:9], off offset:512
	global_store_dwordx4 v[18:19], v[2:5], off offset:528
	s_waitcnt vmcnt(0)
	s_cbranch_scc0 .LBB0_876
	s_barrier

.LBB0_897:
	ds_read_b128 v[146:149], v156
	ds_read_b128 v[150:153], v156 offset:1024
	ds_read_b128 v[160:163], v156 offset:2048
	ds_read_b128 v[164:167], v156 offset:3072
	ds_read_b128 v[168:171], v157
	ds_read_b128 v[172:175], v157 offset:1024
	ds_read_b128 v[176:179], v157 offset:2048
	ds_read_b128 v[180:183], v157 offset:3072
	s_add_u32 s44, s42, 0xffc00080
	s_addc_u32 s45, s43, -1
	s_cmpk_eq_i32 s67, 0xfc
	s_cselect_b32 s47, s35, s45
	s_cselect_b32 s46, s63, s44
	s_cselect_b32 s45, s31, s66
	s_cselect_b32 s44, s64, s65
	s_add_i32 m0, s41, 0xc000
	ds_read_b128 v[184:187], v158
	ds_read_b128 v[188:191], v158 offset:1024
	ds_read_b128 v[192:195], v158 offset:2048
	ds_read_b128 v[198:201], v158 offset:3072
	ds_read_b128 v[202:205], v158 offset:4096
	ds_read_b128 v[206:209], v158 offset:5120
	ds_read_b128 v[210:213], v158 offset:6144
	ds_read_b128 v[214:217], v158 offset:7168
	global_load_lds_dwordx4 v138, s[42:43]
	s_add_i32 m0, s41, 0xe000
	s_nop 0
	global_load_lds_dwordx4 v140, s[42:43]
	s_waitcnt vmcnt(8)
	s_waitcnt lgkmcnt(0)
	s_setprio 1
	s_barrier
	v_mfma_f32_16x16x32_bf16 v[126:129], v[146:149], v[184:187], v[126:129]
	v_mfma_f32_16x16x32_bf16 v[122:125], v[160:163], v[184:187], v[122:125]
	v_mfma_f32_16x16x32_bf16 v[110:113], v[146:149], v[192:195], v[110:113]
	v_mfma_f32_16x16x32_bf16 v[106:109], v[160:163], v[192:195], v[106:109]
	v_mfma_f32_16x16x32_bf16 v[94:97], v[146:149], v[202:205], v[94:97]
	v_mfma_f32_16x16x32_bf16 v[90:93], v[160:163], v[202:205], v[90:93]
	v_mfma_f32_16x16x32_bf16 v[78:81], v[146:149], v[210:213], v[78:81]
	v_mfma_f32_16x16x32_bf16 v[74:77], v[160:163], v[210:213], v[74:77]
	v_mfma_f32_16x16x32_bf16 v[126:129], v[150:153], v[188:191], v[126:129]
	v_mfma_f32_16x16x32_bf16 v[122:125], v[164:167], v[188:191], v[122:125]
	v_mfma_f32_16x16x32_bf16 v[110:113], v[150:153], v[198:201], v[110:113]
	v_mfma_f32_16x16x32_bf16 v[106:109], v[164:167], v[198:201], v[106:109]
	v_mfma_f32_16x16x32_bf16 v[94:97], v[150:153], v[206:209], v[94:97]
	v_mfma_f32_16x16x32_bf16 v[90:93], v[164:167], v[206:209], v[90:93]
	v_mfma_f32_16x16x32_bf16 v[78:81], v[150:153], v[214:217], v[78:81]
	v_mfma_f32_16x16x32_bf16 v[74:77], v[164:167], v[214:217], v[74:77]
	v_mfma_f32_16x16x32_bf16 v[118:121], v[168:171], v[184:187], v[118:121]
	v_mfma_f32_16x16x32_bf16 v[114:117], v[176:179], v[184:187], v[114:117]
	v_mfma_f32_16x16x32_bf16 v[102:105], v[168:171], v[192:195], v[102:105]
	v_mfma_f32_16x16x32_bf16 v[98:101], v[176:179], v[192:195], v[98:101]
	v_mfma_f32_16x16x32_bf16 v[86:89], v[168:171], v[202:205], v[86:89]
	v_mfma_f32_16x16x32_bf16 v[82:85], v[176:179], v[202:205], v[82:85]
	v_mfma_f32_16x16x32_bf16 v[70:73], v[168:171], v[210:213], v[70:73]
	v_mfma_f32_16x16x32_bf16 v[66:69], v[176:179], v[210:213], v[66:69]
	v_mfma_f32_16x16x32_bf16 v[118:121], v[172:175], v[188:191], v[118:121]
	v_mfma_f32_16x16x32_bf16 v[114:117], v[180:183], v[188:191], v[114:117]
	v_mfma_f32_16x16x32_bf16 v[102:105], v[172:175], v[198:201], v[102:105]
	v_mfma_f32_16x16x32_bf16 v[98:101], v[180:183], v[198:201], v[98:101]
	v_mfma_f32_16x16x32_bf16 v[86:89], v[172:175], v[206:209], v[86:89]
	v_mfma_f32_16x16x32_bf16 v[82:85], v[180:183], v[206:209], v[82:85]
	v_mfma_f32_16x16x32_bf16 v[70:73], v[172:175], v[214:217], v[70:73]
	v_mfma_f32_16x16x32_bf16 v[66:69], v[180:183], v[214:217], v[66:69]
	s_barrier
	s_setprio 0
	s_add_i32 s68, s56, s48
	s_mov_b32 m0, s68
	ds_read_b128 v[184:187], v158 offset:16384
	ds_read_b128 v[188:191], v158 offset:17408
	ds_read_b128 v[192:195], v158 offset:18432
	ds_read_b128 v[198:201], v158 offset:19456
	ds_read_b128 v[202:205], v158 offset:20480
	ds_read_b128 v[206:209], v158 offset:21504
	ds_read_b128 v[210:213], v158 offset:22528
	ds_read_b128 v[214:217], v158 offset:23552
	global_load_lds_dwordx4 v132, s[44:45]
	s_add_i32 m0, s68, 0x2000
	s_add_u32 s68, s44, 0x400000
	s_addc_u32 s69, s45, 0
	s_add_i32 s70, s57, s48
	global_load_lds_dwordx4 v136, s[44:45]
	s_mov_b32 m0, s70
	global_load_lds_dwordx4 v132, s[68:69]
	s_add_i32 m0, s70, 0x2000
	s_nop 0
	global_load_lds_dwordx4 v136, s[68:69]
	s_mov_b32 m0, s41
	s_nop 0
	global_load_lds_dwordx4 v130, s[46:47]
	s_mov_b32 m0, s49
	s_nop 0
	global_load_lds_dwordx4 v134, s[46:47]
	s_waitcnt vmcnt(8)
	s_waitcnt lgkmcnt(0)
	s_setprio 1
	s_barrier
	v_mfma_f32_16x16x32_bf16 v[62:65], v[146:149], v[184:187], v[62:65]
	v_mfma_f32_16x16x32_bf16 v[58:61], v[160:163], v[184:187], v[58:61]
	v_mfma_f32_16x16x32_bf16 v[46:49], v[146:149], v[192:195], v[46:49]
	v_mfma_f32_16x16x32_bf16 v[42:45], v[160:163], v[192:195], v[42:45]
	v_mfma_f32_16x16x32_bf16 v[30:33], v[146:149], v[202:205], v[30:33]
	v_mfma_f32_16x16x32_bf16 v[26:29], v[160:163], v[202:205], v[26:29]
	v_mfma_f32_16x16x32_bf16 v[14:17], v[146:149], v[210:213], v[14:17]
	v_mfma_f32_16x16x32_bf16 v[10:13], v[160:163], v[210:213], v[10:13]
	v_mfma_f32_16x16x32_bf16 v[62:65], v[150:153], v[188:191], v[62:65]
	v_mfma_f32_16x16x32_bf16 v[58:61], v[164:167], v[188:191], v[58:61]
	v_mfma_f32_16x16x32_bf16 v[46:49], v[150:153], v[198:201], v[46:49]
	v_mfma_f32_16x16x32_bf16 v[42:45], v[164:167], v[198:201], v[42:45]
	v_mfma_f32_16x16x32_bf16 v[30:33], v[150:153], v[206:209], v[30:33]
	v_mfma_f32_16x16x32_bf16 v[26:29], v[164:167], v[206:209], v[26:29]
	v_mfma_f32_16x16x32_bf16 v[14:17], v[150:153], v[214:217], v[14:17]
	v_mfma_f32_16x16x32_bf16 v[10:13], v[164:167], v[214:217], v[10:13]
	v_mfma_f32_16x16x32_bf16 v[54:57], v[168:171], v[184:187], v[54:57]
	v_mfma_f32_16x16x32_bf16 v[50:53], v[176:179], v[184:187], v[50:53]
	v_mfma_f32_16x16x32_bf16 v[38:41], v[168:171], v[192:195], v[38:41]
	v_mfma_f32_16x16x32_bf16 v[34:37], v[176:179], v[192:195], v[34:37]
	v_mfma_f32_16x16x32_bf16 v[22:25], v[168:171], v[202:205], v[22:25]
	v_mfma_f32_16x16x32_bf16 v[18:21], v[176:179], v[202:205], v[18:21]
	v_mfma_f32_16x16x32_bf16 v[6:9], v[168:171], v[210:213], v[6:9]
	v_mfma_f32_16x16x32_bf16 v[2:5], v[176:179], v[210:213], v[2:5]
	v_mfma_f32_16x16x32_bf16 v[54:57], v[172:175], v[188:191], v[54:57]
	v_mfma_f32_16x16x32_bf16 v[50:53], v[180:183], v[188:191], v[50:53]
	v_mfma_f32_16x16x32_bf16 v[38:41], v[172:175], v[198:201], v[38:41]
	v_mfma_f32_16x16x32_bf16 v[34:37], v[180:183], v[198:201], v[34:37]
	v_mfma_f32_16x16x32_bf16 v[22:25], v[172:175], v[206:209], v[22:25]
	v_mfma_f32_16x16x32_bf16 v[18:21], v[180:183], v[206:209], v[18:21]
	v_mfma_f32_16x16x32_bf16 v[6:9], v[172:175], v[214:217], v[6:9]
	v_mfma_f32_16x16x32_bf16 v[2:5], v[180:183], v[214:217], v[2:5]
	s_barrier
	s_setprio 0
	s_add_i32 s68, 0, 0x18000
	s_add_i32 s69, 0, 0x1c000
	v_add_u32_e32 v164, s68, v154
	v_add_u32_e32 v180, s69, v154
	ds_read_b128 v[146:149], v164
	ds_read_b128 v[150:153], v164 offset:1024
	ds_read_b128 v[160:163], v164 offset:2048
	ds_read_b128 v[164:167], v164 offset:3072
	ds_read_b128 v[168:171], v180
	ds_read_b128 v[172:175], v180 offset:1024
	ds_read_b128 v[176:179], v180 offset:2048
	ds_read_b128 v[180:183], v180 offset:3072
	s_add_u32 s46, s46, 0x400000
	s_addc_u32 s47, s47, 0
	s_mov_b32 m0, s50
	ds_read_b128 v[184:187], v158 offset:32768
	ds_read_b128 v[188:191], v158 offset:33792
	ds_read_b128 v[192:195], v158 offset:34816
	ds_read_b128 v[198:201], v158 offset:35840
	ds_read_b128 v[202:205], v158 offset:36864
	ds_read_b128 v[206:209], v158 offset:37888
	ds_read_b128 v[210:213], v158 offset:38912
	ds_read_b128 v[214:217], v158 offset:39936
	global_load_lds_dwordx4 v130, s[46:47]
	s_mov_b32 m0, s51
	s_nop 0
	global_load_lds_dwordx4 v134, s[46:47]
	s_waitcnt vmcnt(8)
	s_waitcnt lgkmcnt(0)
	s_setprio 1
	s_barrier
	v_mfma_f32_16x16x32_bf16 v[126:129], v[146:149], v[184:187], v[126:129]
	v_mfma_f32_16x16x32_bf16 v[122:125], v[160:163], v[184:187], v[122:125]
	v_mfma_f32_16x16x32_bf16 v[110:113], v[146:149], v[192:195], v[110:113]
	v_mfma_f32_16x16x32_bf16 v[106:109], v[160:163], v[192:195], v[106:109]
	v_mfma_f32_16x16x32_bf16 v[94:97], v[146:149], v[202:205], v[94:97]
	v_mfma_f32_16x16x32_bf16 v[90:93], v[160:163], v[202:205], v[90:93]
	v_mfma_f32_16x16x32_bf16 v[78:81], v[146:149], v[210:213], v[78:81]
	v_mfma_f32_16x16x32_bf16 v[74:77], v[160:163], v[210:213], v[74:77]
	v_mfma_f32_16x16x32_bf16 v[126:129], v[150:153], v[188:191], v[126:129]
	v_mfma_f32_16x16x32_bf16 v[122:125], v[164:167], v[188:191], v[122:125]
	v_mfma_f32_16x16x32_bf16 v[110:113], v[150:153], v[198:201], v[110:113]
	v_mfma_f32_16x16x32_bf16 v[106:109], v[164:167], v[198:201], v[106:109]
	v_mfma_f32_16x16x32_bf16 v[94:97], v[150:153], v[206:209], v[94:97]
	v_mfma_f32_16x16x32_bf16 v[90:93], v[164:167], v[206:209], v[90:93]
	v_mfma_f32_16x16x32_bf16 v[78:81], v[150:153], v[214:217], v[78:81]
	v_mfma_f32_16x16x32_bf16 v[74:77], v[164:167], v[214:217], v[74:77]
	v_mfma_f32_16x16x32_bf16 v[118:121], v[168:171], v[184:187], v[118:121]
	v_mfma_f32_16x16x32_bf16 v[114:117], v[176:179], v[184:187], v[114:117]
	v_mfma_f32_16x16x32_bf16 v[102:105], v[168:171], v[192:195], v[102:105]
	v_mfma_f32_16x16x32_bf16 v[98:101], v[176:179], v[192:195], v[98:101]
	v_mfma_f32_16x16x32_bf16 v[86:89], v[168:171], v[202:205], v[86:89]
	v_mfma_f32_16x16x32_bf16 v[82:85], v[176:179], v[202:205], v[82:85]
	v_mfma_f32_16x16x32_bf16 v[70:73], v[168:171], v[210:213], v[70:73]
	v_mfma_f32_16x16x32_bf16 v[66:69], v[176:179], v[210:213], v[66:69]
	v_mfma_f32_16x16x32_bf16 v[118:121], v[172:175], v[188:191], v[118:121]
	v_mfma_f32_16x16x32_bf16 v[114:117], v[180:183], v[188:191], v[114:117]
	v_mfma_f32_16x16x32_bf16 v[102:105], v[172:175], v[198:201], v[102:105]
	v_mfma_f32_16x16x32_bf16 v[98:101], v[180:183], v[198:201], v[98:101]
	v_mfma_f32_16x16x32_bf16 v[86:89], v[172:175], v[206:209], v[86:89]
	v_mfma_f32_16x16x32_bf16 v[82:85], v[180:183], v[206:209], v[82:85]
	v_mfma_f32_16x16x32_bf16 v[70:73], v[172:175], v[214:217], v[70:73]
	v_mfma_f32_16x16x32_bf16 v[66:69], v[180:183], v[214:217], v[66:69]
	s_barrier
	s_setprio 0
	s_add_u32 s44, s44, 0x80
	s_addc_u32 s45, s45, 0
	s_add_i32 m0, s48, 0x18000
	ds_read_b128 v[184:187], v158 offset:49152
	ds_read_b128 v[188:191], v158 offset:50176
	ds_read_b128 v[192:195], v158 offset:51200
	ds_read_b128 v[198:201], v158 offset:52224
	ds_read_b128 v[202:205], v158 offset:53248
	ds_read_b128 v[206:209], v158 offset:54272
	ds_read_b128 v[210:213], v158 offset:55296
	ds_read_b128 v[214:217], v158 offset:56320
	global_load_lds_dwordx4 v132, s[44:45]
	s_add_i32 m0, s48, 0x1a000
	s_add_u32 s46, s46, 0xffc00080
	global_load_lds_dwordx4 v136, s[44:45]
	s_addc_u32 s47, s47, -1
	s_add_u32 s44, s44, 0x400000
	s_addc_u32 s45, s45, 0
	s_add_i32 m0, s48, 0x1c000
	s_nop 0
	global_load_lds_dwordx4 v132, s[44:45]
	s_add_i32 m0, s48, 0x1e000
	s_nop 0
	global_load_lds_dwordx4 v136, s[44:45]
	s_mov_b32 m0, s53
	s_nop 0
	global_load_lds_dwordx4 v130, s[46:47]
	s_mov_b32 m0, s54
	s_nop 0
	global_load_lds_dwordx4 v134, s[46:47]
	s_waitcnt vmcnt(8)
	s_waitcnt lgkmcnt(0)
	s_setprio 1
	s_barrier
	v_mfma_f32_16x16x32_bf16 v[62:65], v[146:149], v[184:187], v[62:65]
	v_mfma_f32_16x16x32_bf16 v[58:61], v[160:163], v[184:187], v[58:61]
	v_mfma_f32_16x16x32_bf16 v[46:49], v[146:149], v[192:195], v[46:49]
	v_mfma_f32_16x16x32_bf16 v[42:45], v[160:163], v[192:195], v[42:45]
	v_mfma_f32_16x16x32_bf16 v[30:33], v[146:149], v[202:205], v[30:33]
	v_mfma_f32_16x16x32_bf16 v[26:29], v[160:163], v[202:205], v[26:29]
	v_mfma_f32_16x16x32_bf16 v[14:17], v[146:149], v[210:213], v[14:17]
	v_mfma_f32_16x16x32_bf16 v[10:13], v[160:163], v[210:213], v[10:13]
	v_mfma_f32_16x16x32_bf16 v[62:65], v[150:153], v[188:191], v[62:65]
	v_mfma_f32_16x16x32_bf16 v[58:61], v[164:167], v[188:191], v[58:61]
	v_mfma_f32_16x16x32_bf16 v[46:49], v[150:153], v[198:201], v[46:49]
	v_mfma_f32_16x16x32_bf16 v[42:45], v[164:167], v[198:201], v[42:45]
	v_mfma_f32_16x16x32_bf16 v[30:33], v[150:153], v[206:209], v[30:33]
	v_mfma_f32_16x16x32_bf16 v[26:29], v[164:167], v[206:209], v[26:29]
	v_mfma_f32_16x16x32_bf16 v[14:17], v[150:153], v[214:217], v[14:17]
	v_mfma_f32_16x16x32_bf16 v[10:13], v[164:167], v[214:217], v[10:13]
	v_mfma_f32_16x16x32_bf16 v[54:57], v[168:171], v[184:187], v[54:57]
	v_mfma_f32_16x16x32_bf16 v[50:53], v[176:179], v[184:187], v[50:53]
	v_mfma_f32_16x16x32_bf16 v[38:41], v[168:171], v[192:195], v[38:41]
	v_mfma_f32_16x16x32_bf16 v[34:37], v[176:179], v[192:195], v[34:37]
	v_mfma_f32_16x16x32_bf16 v[22:25], v[168:171], v[202:205], v[22:25]
	v_mfma_f32_16x16x32_bf16 v[18:21], v[176:179], v[202:205], v[18:21]
	v_mfma_f32_16x16x32_bf16 v[6:9], v[168:171], v[210:213], v[6:9]
	v_mfma_f32_16x16x32_bf16 v[2:5], v[176:179], v[210:213], v[2:5]
	v_mfma_f32_16x16x32_bf16 v[54:57], v[172:175], v[188:191], v[54:57]
	v_mfma_f32_16x16x32_bf16 v[50:53], v[180:183], v[188:191], v[50:53]
	v_mfma_f32_16x16x32_bf16 v[38:41], v[172:175], v[198:201], v[38:41]
	v_mfma_f32_16x16x32_bf16 v[34:37], v[180:183], v[198:201], v[34:37]
	v_mfma_f32_16x16x32_bf16 v[22:25], v[172:175], v[206:209], v[22:25]
	v_mfma_f32_16x16x32_bf16 v[18:21], v[180:183], v[206:209], v[18:21]
	v_mfma_f32_16x16x32_bf16 v[6:9], v[172:175], v[214:217], v[6:9]
	v_mfma_f32_16x16x32_bf16 v[2:5], v[180:183], v[214:217], v[2:5]
	s_barrier
	s_setprio 0
	s_add_i32 s67, s67, 2
	s_add_u32 s42, s42, 0x100
	s_addc_u32 s43, s43, 0
	s_add_u32 s65, s65, 0x100
	s_addc_u32 s66, s66, 0
	s_cmpk_gt_u32 s67, 0xfd
	s_cbranch_scc0 .LBB0_897
	s_and_b64 vcc, exec, s[14:15]
	s_cbranch_vccz .LBB0_900
	s_barrier
